# index v8f: the next item's A image data, weights and first three B tiles are requested under the previous item's selection (selection keys moved to v88-v151, temps to the accumulator registers)
# speedup vs baseline: 1.0228x; 1.0063x over previous
.LBB0_149:
	s_lshl_b32 s1, s2, 3
	s_lshl_b32 s0, s3, 12
	s_add_i32 s27, s0, s1
	s_ashr_i32 s38, s2, 3
	v_lshrrev_b32_e32 v33, 4, v34
	v_lshlrev_b32_e32 v33, 4, v33
	v_and_b32_e32 v191, 15, v34
	v_lshl_or_b32 v191, v191, 6, v33
	s_lshl_b32 s4, s22, 9
	s_add_i32 s4, s4, 0x22000
	v_add_u32_e32 v164, s4, v33
	v_lshlrev_b32_e32 v166, 10, v33
	v_and_b32_e32 v169, 15, v34
	s_lshl_b32 s4, s22, 6
	v_lshl_add_u32 v166, v169, 2, v166
	v_add_u32_e32 v166, s4, v166
	s_lshl_b32 s4, s22, 8
	s_add_i32 s4, s4, 0x23000
	v_lshl_add_u32 v168, v34, 2, s4
	v_readlane_b32 s4, v253, 11
	v_readlane_b32 s5, v253, 12
	v_readlane_b32 s28, v253, 40
	v_readlane_b32 s29, v253, 41
	v_readlane_b32 s6, v253, 38
	v_readlane_b32 s7, v253, 39
	s_add_u32 s4, s4, 0x1d302200
	s_addc_u32 s5, s5, 0
	s_lshl_b32 s0, s27, 6
	s_add_u32 s28, s28, s0
	s_addc_u32 s29, s29, 0
	v_and_b32_e32 v9, 15, v34
	v_lshrrev_b32_e32 v10, 4, v34
	v_add_u32_e32 v11, 0, v10
	v_xor_b32_e32 v11, v11, v9
	v_lshlrev_b32_e32 v11, 4, v11
	v_lshl_add_u32 v0, v10, 8, v11
	v_add_u32_e32 v0, 0x18000, v0
	v_add_u32_e32 v11, 4, v10
	v_xor_b32_e32 v11, v11, v9
	v_lshlrev_b32_e32 v11, 4, v11
	v_lshl_add_u32 v1, v10, 8, v11
	v_add_u32_e32 v1, 0x18400, v1
	v_add_u32_e32 v11, 8, v10
	v_xor_b32_e32 v11, v11, v9
	v_lshlrev_b32_e32 v11, 4, v11
	v_lshl_add_u32 v2, v10, 8, v11
	v_add_u32_e32 v2, 0x18800, v2
	v_add_u32_e32 v11, 12, v10
	v_xor_b32_e32 v11, v11, v9
	v_lshlrev_b32_e32 v11, 4, v11
	v_lshl_add_u32 v3, v10, 8, v11
	v_add_u32_e32 v3, 0x18c00, v3
	v_lshrrev_b32_e32 v12, 2, v9
	v_and_b32_e32 v13, 3, v9
	v_xor_b32_e32 v14, v10, v13
	v_lshlrev_b32_e32 v15, 10, v12
	v_lshl_add_u32 v15, v13, 8, v15
	s_lshl_b32 s0, s22, 12
	s_add_i32 s0, s0, 0x18000
	v_add_u32_e32 v15, s0, v15
	v_xor_b32_e32 v16, 0, v12
	v_lshl_add_u32 v16, v16, 2, v14
	v_lshl_add_u32 v4, v16, 4, v15
	v_xor_b32_e32 v16, 1, v12
	v_lshl_add_u32 v16, v16, 2, v14
	v_lshl_add_u32 v5, v16, 4, v15
	v_xor_b32_e32 v16, 2, v12
	v_lshl_add_u32 v16, v16, 2, v14
	v_lshl_add_u32 v6, v16, 4, v15
	v_xor_b32_e32 v16, 3, v12
	v_lshl_add_u32 v16, v16, 2, v14
	v_lshl_add_u32 v7, v16, 4, v15
	v_lshlrev_b32_e32 v35, 4, v34
	s_cmp_lg_u32 s82, 0
	s_cbranch_scc1 .Lix_skipA
	s_lshl_b32 s0, s3, 20
	s_lshl_b32 s1, s22, 12
	s_add_u32 s46, s6, s0
	s_addc_u32 s47, s7, 0
	s_add_u32 s46, s46, s1
	s_addc_u32 s47, s47, 0
	global_load_dwordx4 v[196:199], v191, s[46:47]
	global_load_dwordx4 v[200:203], v191, s[46:47] offset:1024
	global_load_dwordx4 v[204:207], v191, s[46:47] offset:2048
	global_load_dwordx4 v[208:211], v191, s[46:47] offset:3072
	s_add_u32 s46, s46, 0x8000
	s_addc_u32 s47, s47, 0
	global_load_dwordx4 v[212:215], v191, s[46:47]
	global_load_dwordx4 v[216:219], v191, s[46:47] offset:1024
	global_load_dwordx4 v[220:223], v191, s[46:47] offset:2048
	global_load_dwordx4 v[224:227], v191, s[46:47] offset:3072
	s_add_u32 s46, s46, 0x8000
	s_addc_u32 s47, s47, 0
	global_load_dwordx4 v[228:231], v191, s[46:47]
	global_load_dwordx4 v[232:235], v191, s[46:47] offset:1024
	global_load_dwordx4 v[236:239], v191, s[46:47] offset:2048
	global_load_dwordx4 v[240:243], v191, s[46:47] offset:3072
	s_add_u32 s46, s46, 0x8000
	s_addc_u32 s47, s47, 0
	global_load_dwordx4 v[56:59], v33, s[28:29]
	global_load_dwordx4 v[60:63], v33, s[28:29] offset:64
	global_load_dwordx4 v[64:67], v33, s[28:29] offset:128
	global_load_dwordx4 v[68:71], v33, s[28:29] offset:192
	global_load_dwordx4 v[72:75], v33, s[28:29] offset:256
	global_load_dwordx4 v[76:79], v33, s[28:29] offset:320
	global_load_dwordx4 v[80:83], v33, s[28:29] offset:384
	global_load_dwordx4 v[84:87], v33, s[28:29] offset:448
	s_add_i32 s30, s27, s22
	s_mul_i32 s30, s30, 0x3400
	s_add_u32 s30, s4, s30
	s_addc_u32 s31, s5, 0
	global_load_dwordx4 v[40:43], v35, s[30:31]
	global_load_dwordx4 v[44:47], v35, s[30:31] offset:1024
	global_load_dwordx4 v[48:51], v35, s[30:31] offset:2048
	global_load_dwordx4 v[52:55], v35, s[30:31] offset:3072
.Lix_skipA:
	s_waitcnt vmcnt(0)
	ds_write_b128 v4, v[40:43]
	ds_write_b128 v5, v[44:47]
	ds_write_b128 v6, v[48:51]
	ds_write_b128 v7, v[52:55]
	ds_write_b128 v164, v[56:59]
	ds_write_b128 v164, v[60:63] offset:64
	ds_write_b128 v164, v[64:67] offset:128
	ds_write_b128 v164, v[68:71] offset:192
	ds_write_b128 v164, v[72:75] offset:256
	ds_write_b128 v164, v[76:79] offset:320
	ds_write_b128 v164, v[80:83] offset:384
	ds_write_b128 v164, v[84:87] offset:448
	s_waitcnt lgkmcnt(0)
	s_barrier
	ds_read_b128 v[40:43], v0
	ds_read_b128 v[44:47], v1
	ds_read_b128 v[48:51], v2
	ds_read_b128 v[52:55], v3
	ds_read_b128 v[56:59], v0 offset:4096
	ds_read_b128 v[60:63], v1 offset:4096
	ds_read_b128 v[64:67], v2 offset:4096
	ds_read_b128 v[68:71], v3 offset:4096
	ds_read_b128 v[72:75], v0 offset:8192
	ds_read_b128 v[76:79], v1 offset:8192
	ds_read_b128 v[80:83], v2 offset:8192
	ds_read_b128 v[84:87], v3 offset:8192
	ds_read_b128 v[88:91], v0 offset:12288
	ds_read_b128 v[92:95], v1 offset:12288
	ds_read_b128 v[96:99], v2 offset:12288
	ds_read_b128 v[100:103], v3 offset:12288
	ds_read_b128 v[104:107], v0 offset:16384
	ds_read_b128 v[108:111], v1 offset:16384
	ds_read_b128 v[112:115], v2 offset:16384
	ds_read_b128 v[116:119], v3 offset:16384
	ds_read_b128 v[120:123], v0 offset:20480
	ds_read_b128 v[124:127], v1 offset:20480
	ds_read_b128 v[128:131], v2 offset:20480
	ds_read_b128 v[132:135], v3 offset:20480
	ds_read_b128 v[136:139], v0 offset:24576
	ds_read_b128 v[140:143], v1 offset:24576
	ds_read_b128 v[144:147], v2 offset:24576
	ds_read_b128 v[148:151], v3 offset:24576
	ds_read_b128 v[152:155], v0 offset:28672
	ds_read_b128 v[156:159], v1 offset:28672
	ds_read_b128 v[160:163], v2 offset:28672
	ds_read_b128 v[192:195], v3 offset:28672
	s_lshl_b32 s36, s38, 2
	s_add_i32 s36, s36, 11
	s_sub_i32 s36, s36, s22
	s_lshr_b32 s36, s36, 3
	s_waitcnt lgkmcnt(0)
	s_barrier
	ds_read_b128 v[172:175], v164 offset:256
	ds_read_b128 v[244:247], v164 offset:320
.Lix_loop:
	s_cmp_eq_u32 s36, 0
	s_cbranch_scc1 .Lix_done
	s_waitcnt vmcnt(8)
	v_mfma_f32_16x16x32_bf16 v[0:3], v[40:43], v[196:199], 0
	s_waitcnt lgkmcnt(1)
	v_max_f32_e32 v16, 0, v16
	v_max_f32_e32 v17, 0, v17
	v_max_f32_e32 v18, 0, v18
	v_mfma_f32_16x16x32_bf16 v[4:7], v[56:59], v[196:199], 0
	v_max_f32_e32 v19, 0, v19
	v_mul_f32_e32 v169, v172, v16
	v_fmac_f32_e32 v169, v173, v17
	v_fmac_f32_e32 v169, v174, v18
	v_mfma_f32_16x16x32_bf16 v[8:11], v[72:75], v[196:199], 0
	v_fmac_f32_e32 v169, v175, v19
	ds_read_b128 v[172:175], v164 offset:384
	s_waitcnt lgkmcnt(1)
	v_max_f32_e32 v20, 0, v20
	v_mfma_f32_16x16x32_bf16 v[12:15], v[88:91], v[196:199], 0
	v_max_f32_e32 v21, 0, v21
	v_max_f32_e32 v22, 0, v22
	v_max_f32_e32 v23, 0, v23
	v_mul_f32_e32 v170, v244, v20
	v_mfma_f32_16x16x32_bf16 v[0:3], v[44:47], v[200:203], v[0:3]
	v_fmac_f32_e32 v170, v245, v21
	v_fmac_f32_e32 v170, v246, v22
	v_fmac_f32_e32 v170, v247, v23
	ds_read_b128 v[244:247], v164 offset:448
	v_mfma_f32_16x16x32_bf16 v[4:7], v[60:63], v[200:203], v[4:7]
	s_waitcnt lgkmcnt(1)
	v_max_f32_e32 v24, 0, v24
	v_max_f32_e32 v25, 0, v25
	v_max_f32_e32 v26, 0, v26
	v_mfma_f32_16x16x32_bf16 v[8:11], v[76:79], v[200:203], v[8:11]
	v_max_f32_e32 v27, 0, v27
	v_mul_f32_e32 v176, v172, v24
	v_fmac_f32_e32 v176, v173, v25
	v_fmac_f32_e32 v176, v174, v26
	v_mfma_f32_16x16x32_bf16 v[12:15], v[92:95], v[200:203], v[12:15]
	v_fmac_f32_e32 v176, v175, v27
	s_waitcnt lgkmcnt(0)
	v_max_f32_e32 v28, 0, v28
	v_max_f32_e32 v29, 0, v29
	v_mfma_f32_16x16x32_bf16 v[0:3], v[48:51], v[204:207], v[0:3]
	v_max_f32_e32 v30, 0, v30
	v_max_f32_e32 v31, 0, v31
	v_mul_f32_e32 v177, v244, v28
	v_fmac_f32_e32 v177, v245, v29
	v_mfma_f32_16x16x32_bf16 v[4:7], v[64:67], v[204:207], v[4:7]
	v_fmac_f32_e32 v177, v246, v30
	v_fmac_f32_e32 v177, v247, v31
	s_nop 1
	v_permlane16_swap_b32 v169, v170
	v_mfma_f32_16x16x32_bf16 v[8:11], v[80:83], v[204:207], v[8:11]
	v_permlane16_swap_b32 v176, v177
	v_add_f32_e32 v169, v169, v170
	v_add_f32_e32 v176, v176, v177
	s_nop 1
	v_mfma_f32_16x16x32_bf16 v[12:15], v[96:99], v[204:207], v[12:15]
	v_permlane32_swap_b32 v169, v176
	v_add_f32_e32 v169, v169, v176
	ds_write_b32 v168, v169
	ds_read_b128 v[172:175], v164
	v_mfma_f32_16x16x32_bf16 v[0:3], v[52:55], v[208:211], v[0:3]
	ds_read_b128 v[244:247], v164 offset:64
	v_mfma_f32_16x16x32_bf16 v[4:7], v[68:71], v[208:211], v[4:7]
	v_mfma_f32_16x16x32_bf16 v[8:11], v[84:87], v[208:211], v[8:11]
	v_mfma_f32_16x16x32_bf16 v[12:15], v[100:103], v[208:211], v[12:15]
	v_mfma_f32_16x16x32_bf16 v[16:19], v[104:107], v[196:199], 0
	s_waitcnt lgkmcnt(1)
	v_max_f32_e32 v0, 0, v0
	v_max_f32_e32 v1, 0, v1
	v_max_f32_e32 v2, 0, v2
	v_mfma_f32_16x16x32_bf16 v[20:23], v[120:123], v[196:199], 0
	v_max_f32_e32 v3, 0, v3
	v_mul_f32_e32 v169, v172, v0
	v_fmac_f32_e32 v169, v173, v1
	v_fmac_f32_e32 v169, v174, v2
	v_mfma_f32_16x16x32_bf16 v[24:27], v[136:139], v[196:199], 0
	v_fmac_f32_e32 v169, v175, v3
	ds_read_b128 v[172:175], v164 offset:128
	s_waitcnt lgkmcnt(1)
	v_max_f32_e32 v4, 0, v4
	v_mfma_f32_16x16x32_bf16 v[28:31], v[152:155], v[196:199], 0
	v_max_f32_e32 v5, 0, v5
	v_max_f32_e32 v6, 0, v6
	v_max_f32_e32 v7, 0, v7
	v_mul_f32_e32 v170, v244, v4
	v_mfma_f32_16x16x32_bf16 v[16:19], v[108:111], v[200:203], v[16:19]
	v_fmac_f32_e32 v170, v245, v5
	v_fmac_f32_e32 v170, v246, v6
	v_fmac_f32_e32 v170, v247, v7
	ds_read_b128 v[244:247], v164 offset:192
	v_mfma_f32_16x16x32_bf16 v[20:23], v[124:127], v[200:203], v[20:23]
	s_waitcnt lgkmcnt(1)
	v_max_f32_e32 v8, 0, v8
	v_max_f32_e32 v9, 0, v9
	v_max_f32_e32 v10, 0, v10
	v_mfma_f32_16x16x32_bf16 v[24:27], v[140:143], v[200:203], v[24:27]
	v_max_f32_e32 v11, 0, v11
	v_mul_f32_e32 v176, v172, v8
	v_fmac_f32_e32 v176, v173, v9
	v_fmac_f32_e32 v176, v174, v10
	v_mfma_f32_16x16x32_bf16 v[28:31], v[156:159], v[200:203], v[28:31]
	v_fmac_f32_e32 v176, v175, v11
	s_waitcnt lgkmcnt(0)
	v_max_f32_e32 v12, 0, v12
	v_max_f32_e32 v13, 0, v13
	v_mfma_f32_16x16x32_bf16 v[16:19], v[112:115], v[204:207], v[16:19]
	v_max_f32_e32 v14, 0, v14
	v_max_f32_e32 v15, 0, v15
	v_mul_f32_e32 v177, v244, v12
	v_fmac_f32_e32 v177, v245, v13
	v_mfma_f32_16x16x32_bf16 v[20:23], v[128:131], v[204:207], v[20:23]
	v_fmac_f32_e32 v177, v246, v14
	v_fmac_f32_e32 v177, v247, v15
	s_nop 1
	v_permlane16_swap_b32 v169, v170
	v_mfma_f32_16x16x32_bf16 v[24:27], v[144:147], v[204:207], v[24:27]
	v_permlane16_swap_b32 v176, v177
	v_add_f32_e32 v169, v169, v170
	v_add_f32_e32 v176, v176, v177
	s_nop 1
	v_mfma_f32_16x16x32_bf16 v[28:31], v[160:163], v[204:207], v[28:31]
	v_permlane32_swap_b32 v169, v176
	v_add_f32_e32 v169, v169, v176
	ds_write_b32 v166, v169
	ds_read_b128 v[172:175], v164 offset:256
	v_mfma_f32_16x16x32_bf16 v[16:19], v[116:119], v[208:211], v[16:19]
	ds_read_b128 v[244:247], v164 offset:320
	v_mfma_f32_16x16x32_bf16 v[20:23], v[132:135], v[208:211], v[20:23]
	v_mfma_f32_16x16x32_bf16 v[24:27], v[148:151], v[208:211], v[24:27]
	v_mfma_f32_16x16x32_bf16 v[28:31], v[192:195], v[208:211], v[28:31]
	global_load_dwordx4 v[196:199], v191, s[46:47]
	global_load_dwordx4 v[200:203], v191, s[46:47] offset:1024
	global_load_dwordx4 v[204:207], v191, s[46:47] offset:2048
	global_load_dwordx4 v[208:211], v191, s[46:47] offset:3072
	s_add_u32 s46, s46, 0x8000
	s_addc_u32 s47, s47, 0
	v_add_u32_e32 v168, 0x10000, v166
	v_add_u32_e32 v166, 0x200, v166
	s_add_i32 s36, s36, -1
	s_cmp_eq_u32 s36, 0
	s_cbranch_scc1 .Lix_done
	s_waitcnt vmcnt(8)
	v_mfma_f32_16x16x32_bf16 v[0:3], v[40:43], v[212:215], 0
	s_waitcnt lgkmcnt(1)
	v_max_f32_e32 v16, 0, v16
	v_max_f32_e32 v17, 0, v17
	v_max_f32_e32 v18, 0, v18
	v_mfma_f32_16x16x32_bf16 v[4:7], v[56:59], v[212:215], 0
	v_max_f32_e32 v19, 0, v19
	v_mul_f32_e32 v169, v172, v16
	v_fmac_f32_e32 v169, v173, v17
	v_fmac_f32_e32 v169, v174, v18
	v_mfma_f32_16x16x32_bf16 v[8:11], v[72:75], v[212:215], 0
	v_fmac_f32_e32 v169, v175, v19
	ds_read_b128 v[172:175], v164 offset:384
	s_waitcnt lgkmcnt(1)
	v_max_f32_e32 v20, 0, v20
	v_mfma_f32_16x16x32_bf16 v[12:15], v[88:91], v[212:215], 0
	v_max_f32_e32 v21, 0, v21
	v_max_f32_e32 v22, 0, v22
	v_max_f32_e32 v23, 0, v23
	v_mul_f32_e32 v170, v244, v20
	v_mfma_f32_16x16x32_bf16 v[0:3], v[44:47], v[216:219], v[0:3]
	v_fmac_f32_e32 v170, v245, v21
	v_fmac_f32_e32 v170, v246, v22
	v_fmac_f32_e32 v170, v247, v23
	ds_read_b128 v[244:247], v164 offset:448
	v_mfma_f32_16x16x32_bf16 v[4:7], v[60:63], v[216:219], v[4:7]
	s_waitcnt lgkmcnt(1)
	v_max_f32_e32 v24, 0, v24
	v_max_f32_e32 v25, 0, v25
	v_max_f32_e32 v26, 0, v26
	v_mfma_f32_16x16x32_bf16 v[8:11], v[76:79], v[216:219], v[8:11]
	v_max_f32_e32 v27, 0, v27
	v_mul_f32_e32 v176, v172, v24
	v_fmac_f32_e32 v176, v173, v25
	v_fmac_f32_e32 v176, v174, v26
	v_mfma_f32_16x16x32_bf16 v[12:15], v[92:95], v[216:219], v[12:15]
	v_fmac_f32_e32 v176, v175, v27
	s_waitcnt lgkmcnt(0)
	v_max_f32_e32 v28, 0, v28
	v_max_f32_e32 v29, 0, v29
	v_mfma_f32_16x16x32_bf16 v[0:3], v[48:51], v[220:223], v[0:3]
	v_max_f32_e32 v30, 0, v30
	v_max_f32_e32 v31, 0, v31
	v_mul_f32_e32 v177, v244, v28
	v_fmac_f32_e32 v177, v245, v29
	v_mfma_f32_16x16x32_bf16 v[4:7], v[64:67], v[220:223], v[4:7]
	v_fmac_f32_e32 v177, v246, v30
	v_fmac_f32_e32 v177, v247, v31
	s_nop 1
	v_permlane16_swap_b32 v169, v170
	v_mfma_f32_16x16x32_bf16 v[8:11], v[80:83], v[220:223], v[8:11]
	v_permlane16_swap_b32 v176, v177
	v_add_f32_e32 v169, v169, v170
	v_add_f32_e32 v176, v176, v177
	s_nop 1
	v_mfma_f32_16x16x32_bf16 v[12:15], v[96:99], v[220:223], v[12:15]
	v_permlane32_swap_b32 v169, v176
	v_add_f32_e32 v169, v169, v176
	ds_write_b32 v168, v169
	ds_read_b128 v[172:175], v164
	v_mfma_f32_16x16x32_bf16 v[0:3], v[52:55], v[224:227], v[0:3]
	ds_read_b128 v[244:247], v164 offset:64
	v_mfma_f32_16x16x32_bf16 v[4:7], v[68:71], v[224:227], v[4:7]
	v_mfma_f32_16x16x32_bf16 v[8:11], v[84:87], v[224:227], v[8:11]
	v_mfma_f32_16x16x32_bf16 v[12:15], v[100:103], v[224:227], v[12:15]
	v_mfma_f32_16x16x32_bf16 v[16:19], v[104:107], v[212:215], 0
	s_waitcnt lgkmcnt(1)
	v_max_f32_e32 v0, 0, v0
	v_max_f32_e32 v1, 0, v1
	v_max_f32_e32 v2, 0, v2
	v_mfma_f32_16x16x32_bf16 v[20:23], v[120:123], v[212:215], 0
	v_max_f32_e32 v3, 0, v3
	v_mul_f32_e32 v169, v172, v0
	v_fmac_f32_e32 v169, v173, v1
	v_fmac_f32_e32 v169, v174, v2
	v_mfma_f32_16x16x32_bf16 v[24:27], v[136:139], v[212:215], 0
	v_fmac_f32_e32 v169, v175, v3
	ds_read_b128 v[172:175], v164 offset:128
	s_waitcnt lgkmcnt(1)
	v_max_f32_e32 v4, 0, v4
	v_mfma_f32_16x16x32_bf16 v[28:31], v[152:155], v[212:215], 0
	v_max_f32_e32 v5, 0, v5
	v_max_f32_e32 v6, 0, v6
	v_max_f32_e32 v7, 0, v7
	v_mul_f32_e32 v170, v244, v4
	v_mfma_f32_16x16x32_bf16 v[16:19], v[108:111], v[216:219], v[16:19]
	v_fmac_f32_e32 v170, v245, v5
	v_fmac_f32_e32 v170, v246, v6
	v_fmac_f32_e32 v170, v247, v7
	ds_read_b128 v[244:247], v164 offset:192
	v_mfma_f32_16x16x32_bf16 v[20:23], v[124:127], v[216:219], v[20:23]
	s_waitcnt lgkmcnt(1)
	v_max_f32_e32 v8, 0, v8
	v_max_f32_e32 v9, 0, v9
	v_max_f32_e32 v10, 0, v10
	v_mfma_f32_16x16x32_bf16 v[24:27], v[140:143], v[216:219], v[24:27]
	v_max_f32_e32 v11, 0, v11
	v_mul_f32_e32 v176, v172, v8
	v_fmac_f32_e32 v176, v173, v9
	v_fmac_f32_e32 v176, v174, v10
	v_mfma_f32_16x16x32_bf16 v[28:31], v[156:159], v[216:219], v[28:31]
	v_fmac_f32_e32 v176, v175, v11
	s_waitcnt lgkmcnt(0)
	v_max_f32_e32 v12, 0, v12
	v_max_f32_e32 v13, 0, v13
	v_mfma_f32_16x16x32_bf16 v[16:19], v[112:115], v[220:223], v[16:19]
	v_max_f32_e32 v14, 0, v14
	v_max_f32_e32 v15, 0, v15
	v_mul_f32_e32 v177, v244, v12
	v_fmac_f32_e32 v177, v245, v13
	v_mfma_f32_16x16x32_bf16 v[20:23], v[128:131], v[220:223], v[20:23]
	v_fmac_f32_e32 v177, v246, v14
	v_fmac_f32_e32 v177, v247, v15
	s_nop 1
	v_permlane16_swap_b32 v169, v170
	v_mfma_f32_16x16x32_bf16 v[24:27], v[144:147], v[220:223], v[24:27]
	v_permlane16_swap_b32 v176, v177
	v_add_f32_e32 v169, v169, v170
	v_add_f32_e32 v176, v176, v177
	s_nop 1
	v_mfma_f32_16x16x32_bf16 v[28:31], v[160:163], v[220:223], v[28:31]
	v_permlane32_swap_b32 v169, v176
	v_add_f32_e32 v169, v169, v176
	ds_write_b32 v166, v169
	ds_read_b128 v[172:175], v164 offset:256
	v_mfma_f32_16x16x32_bf16 v[16:19], v[116:119], v[224:227], v[16:19]
	ds_read_b128 v[244:247], v164 offset:320
	v_mfma_f32_16x16x32_bf16 v[20:23], v[132:135], v[224:227], v[20:23]
	v_mfma_f32_16x16x32_bf16 v[24:27], v[148:151], v[224:227], v[24:27]
	v_mfma_f32_16x16x32_bf16 v[28:31], v[192:195], v[224:227], v[28:31]
	global_load_dwordx4 v[212:215], v191, s[46:47]
	global_load_dwordx4 v[216:219], v191, s[46:47] offset:1024
	global_load_dwordx4 v[220:223], v191, s[46:47] offset:2048
	global_load_dwordx4 v[224:227], v191, s[46:47] offset:3072
	s_add_u32 s46, s46, 0x8000
	s_addc_u32 s47, s47, 0
	v_add_u32_e32 v168, 0x10000, v166
	v_add_u32_e32 v166, 0x200, v166
	s_add_i32 s36, s36, -1
	s_cmp_eq_u32 s36, 0
	s_cbranch_scc1 .Lix_done
	s_waitcnt vmcnt(8)
	v_mfma_f32_16x16x32_bf16 v[0:3], v[40:43], v[228:231], 0
	s_waitcnt lgkmcnt(1)
	v_max_f32_e32 v16, 0, v16
	v_max_f32_e32 v17, 0, v17
	v_max_f32_e32 v18, 0, v18
	v_mfma_f32_16x16x32_bf16 v[4:7], v[56:59], v[228:231], 0
	v_max_f32_e32 v19, 0, v19
	v_mul_f32_e32 v169, v172, v16
	v_fmac_f32_e32 v169, v173, v17
	v_fmac_f32_e32 v169, v174, v18
	v_mfma_f32_16x16x32_bf16 v[8:11], v[72:75], v[228:231], 0
	v_fmac_f32_e32 v169, v175, v19
	ds_read_b128 v[172:175], v164 offset:384
	s_waitcnt lgkmcnt(1)
	v_max_f32_e32 v20, 0, v20
	v_mfma_f32_16x16x32_bf16 v[12:15], v[88:91], v[228:231], 0
	v_max_f32_e32 v21, 0, v21
	v_max_f32_e32 v22, 0, v22
	v_max_f32_e32 v23, 0, v23
	v_mul_f32_e32 v170, v244, v20
	v_mfma_f32_16x16x32_bf16 v[0:3], v[44:47], v[232:235], v[0:3]
	v_fmac_f32_e32 v170, v245, v21
	v_fmac_f32_e32 v170, v246, v22
	v_fmac_f32_e32 v170, v247, v23
	ds_read_b128 v[244:247], v164 offset:448
	v_mfma_f32_16x16x32_bf16 v[4:7], v[60:63], v[232:235], v[4:7]
	s_waitcnt lgkmcnt(1)
	v_max_f32_e32 v24, 0, v24
	v_max_f32_e32 v25, 0, v25
	v_max_f32_e32 v26, 0, v26
	v_mfma_f32_16x16x32_bf16 v[8:11], v[76:79], v[232:235], v[8:11]
	v_max_f32_e32 v27, 0, v27
	v_mul_f32_e32 v176, v172, v24
	v_fmac_f32_e32 v176, v173, v25
	v_fmac_f32_e32 v176, v174, v26
	v_mfma_f32_16x16x32_bf16 v[12:15], v[92:95], v[232:235], v[12:15]
	v_fmac_f32_e32 v176, v175, v27
	s_waitcnt lgkmcnt(0)
	v_max_f32_e32 v28, 0, v28
	v_max_f32_e32 v29, 0, v29
	v_mfma_f32_16x16x32_bf16 v[0:3], v[48:51], v[236:239], v[0:3]
	v_max_f32_e32 v30, 0, v30
	v_max_f32_e32 v31, 0, v31
	v_mul_f32_e32 v177, v244, v28
	v_fmac_f32_e32 v177, v245, v29
	v_mfma_f32_16x16x32_bf16 v[4:7], v[64:67], v[236:239], v[4:7]
	v_fmac_f32_e32 v177, v246, v30
	v_fmac_f32_e32 v177, v247, v31
	s_nop 1
	v_permlane16_swap_b32 v169, v170
	v_mfma_f32_16x16x32_bf16 v[8:11], v[80:83], v[236:239], v[8:11]
	v_permlane16_swap_b32 v176, v177
	v_add_f32_e32 v169, v169, v170
	v_add_f32_e32 v176, v176, v177
	s_nop 1
	v_mfma_f32_16x16x32_bf16 v[12:15], v[96:99], v[236:239], v[12:15]
	v_permlane32_swap_b32 v169, v176
	v_add_f32_e32 v169, v169, v176
	ds_write_b32 v168, v169
	ds_read_b128 v[172:175], v164
	v_mfma_f32_16x16x32_bf16 v[0:3], v[52:55], v[240:243], v[0:3]
	ds_read_b128 v[244:247], v164 offset:64
	v_mfma_f32_16x16x32_bf16 v[4:7], v[68:71], v[240:243], v[4:7]
	v_mfma_f32_16x16x32_bf16 v[8:11], v[84:87], v[240:243], v[8:11]
	v_mfma_f32_16x16x32_bf16 v[12:15], v[100:103], v[240:243], v[12:15]
	v_mfma_f32_16x16x32_bf16 v[16:19], v[104:107], v[228:231], 0
	s_waitcnt lgkmcnt(1)
	v_max_f32_e32 v0, 0, v0
	v_max_f32_e32 v1, 0, v1
	v_max_f32_e32 v2, 0, v2
	v_mfma_f32_16x16x32_bf16 v[20:23], v[120:123], v[228:231], 0
	v_max_f32_e32 v3, 0, v3
	v_mul_f32_e32 v169, v172, v0
	v_fmac_f32_e32 v169, v173, v1
	v_fmac_f32_e32 v169, v174, v2
	v_mfma_f32_16x16x32_bf16 v[24:27], v[136:139], v[228:231], 0
	v_fmac_f32_e32 v169, v175, v3
	ds_read_b128 v[172:175], v164 offset:128
	s_waitcnt lgkmcnt(1)
	v_max_f32_e32 v4, 0, v4
	v_mfma_f32_16x16x32_bf16 v[28:31], v[152:155], v[228:231], 0
	v_max_f32_e32 v5, 0, v5
	v_max_f32_e32 v6, 0, v6
	v_max_f32_e32 v7, 0, v7
	v_mul_f32_e32 v170, v244, v4
	v_mfma_f32_16x16x32_bf16 v[16:19], v[108:111], v[232:235], v[16:19]
	v_fmac_f32_e32 v170, v245, v5
	v_fmac_f32_e32 v170, v246, v6
	v_fmac_f32_e32 v170, v247, v7
	ds_read_b128 v[244:247], v164 offset:192
	v_mfma_f32_16x16x32_bf16 v[20:23], v[124:127], v[232:235], v[20:23]
	s_waitcnt lgkmcnt(1)
	v_max_f32_e32 v8, 0, v8
	v_max_f32_e32 v9, 0, v9
	v_max_f32_e32 v10, 0, v10
	v_mfma_f32_16x16x32_bf16 v[24:27], v[140:143], v[232:235], v[24:27]
	v_max_f32_e32 v11, 0, v11
	v_mul_f32_e32 v176, v172, v8
	v_fmac_f32_e32 v176, v173, v9
	v_fmac_f32_e32 v176, v174, v10
	v_mfma_f32_16x16x32_bf16 v[28:31], v[156:159], v[232:235], v[28:31]
	v_fmac_f32_e32 v176, v175, v11
	s_waitcnt lgkmcnt(0)
	v_max_f32_e32 v12, 0, v12
	v_max_f32_e32 v13, 0, v13
	v_mfma_f32_16x16x32_bf16 v[16:19], v[112:115], v[236:239], v[16:19]
	v_max_f32_e32 v14, 0, v14
	v_max_f32_e32 v15, 0, v15
	v_mul_f32_e32 v177, v244, v12
	v_fmac_f32_e32 v177, v245, v13
	v_mfma_f32_16x16x32_bf16 v[20:23], v[128:131], v[236:239], v[20:23]
	v_fmac_f32_e32 v177, v246, v14
	v_fmac_f32_e32 v177, v247, v15
	s_nop 1
	v_permlane16_swap_b32 v169, v170
	v_mfma_f32_16x16x32_bf16 v[24:27], v[144:147], v[236:239], v[24:27]
	v_permlane16_swap_b32 v176, v177
	v_add_f32_e32 v169, v169, v170
	v_add_f32_e32 v176, v176, v177
	s_nop 1
	v_mfma_f32_16x16x32_bf16 v[28:31], v[160:163], v[236:239], v[28:31]
	v_permlane32_swap_b32 v169, v176
	v_add_f32_e32 v169, v169, v176
	ds_write_b32 v166, v169
	ds_read_b128 v[172:175], v164 offset:256
	v_mfma_f32_16x16x32_bf16 v[16:19], v[116:119], v[240:243], v[16:19]
	ds_read_b128 v[244:247], v164 offset:320
	v_mfma_f32_16x16x32_bf16 v[20:23], v[132:135], v[240:243], v[20:23]
	v_mfma_f32_16x16x32_bf16 v[24:27], v[148:151], v[240:243], v[24:27]
	v_mfma_f32_16x16x32_bf16 v[28:31], v[192:195], v[240:243], v[28:31]
	global_load_dwordx4 v[228:231], v191, s[46:47]
	global_load_dwordx4 v[232:235], v191, s[46:47] offset:1024
	global_load_dwordx4 v[236:239], v191, s[46:47] offset:2048
	global_load_dwordx4 v[240:243], v191, s[46:47] offset:3072
	s_add_u32 s46, s46, 0x8000
	s_addc_u32 s47, s47, 0
	v_add_u32_e32 v168, 0x10000, v166
	v_add_u32_e32 v166, 0x200, v166
	s_add_i32 s36, s36, -1
	s_branch .Lix_loop

.LBB0_160:
	s_waitcnt lgkmcnt(0)
	s_barrier
	s_add_i32 s2, s27, s22
	s_ashr_i32 s3, s2, 31
	s_lshl_b64 s[2:3], s[2:3], 10
	s_add_u32 s2, s26, s2
	s_addc_u32 s3, s76, s3
	v_lshlrev_b32_e32 v28, 2, v34
	s_add_i32 s4, s82, 1
	v_readlane_b32 s5, v253, 3
	v_readlane_b32 s0, v253, 42
	v_readlane_b32 s1, v253, 43
	v_readlane_b32 s7, v253, 44
	s_mul_i32 s6, s4, s5
	s_add_i32 s6, s6, s10
	s_cmpk_gt_i32 s6, 0x7ff
	s_cbranch_scc1 .Lsel_nopfA
	s_lshr_b32 s30, s4, 1
	s_bitcmp0_b32 s4, 0
	s_cselect_b32 s31, s10, s7
	s_cmp_eq_u64 s[0:1], 0
	s_cbranch_scc1 .Lsel_pfA_dec
	s_ashr_i32 s30, s6, 9
	s_and_b32 s31, s6, 0x1ff
.Lsel_pfA_dec:
	s_lshl_b32 s30, s30, 12
	s_lshl_b32 s31, s31, 3
	s_add_i32 s29, s30, s31
	v_readlane_b32 s6, v253, 38
	v_readlane_b32 s7, v253, 39
	s_lshl_b32 s0, s30, 8
	s_lshl_b32 s1, s22, 12
	s_add_u32 s46, s6, s0
	s_addc_u32 s47, s7, 0
	s_add_u32 s46, s46, s1
	s_addc_u32 s47, s47, 0
	global_load_dwordx4 v[196:199], v191, s[46:47]
	global_load_dwordx4 v[200:203], v191, s[46:47] offset:1024
	global_load_dwordx4 v[204:207], v191, s[46:47] offset:2048
	global_load_dwordx4 v[208:211], v191, s[46:47] offset:3072
	s_add_u32 s46, s46, 0x8000
	s_addc_u32 s47, s47, 0
	global_load_dwordx4 v[212:215], v191, s[46:47]
	global_load_dwordx4 v[216:219], v191, s[46:47] offset:1024
	global_load_dwordx4 v[220:223], v191, s[46:47] offset:2048
	global_load_dwordx4 v[224:227], v191, s[46:47] offset:3072
	s_add_u32 s46, s46, 0x8000
	s_addc_u32 s47, s47, 0
	global_load_dwordx4 v[228:231], v191, s[46:47]
	global_load_dwordx4 v[232:235], v191, s[46:47] offset:1024
	global_load_dwordx4 v[236:239], v191, s[46:47] offset:2048
	global_load_dwordx4 v[240:243], v191, s[46:47] offset:3072
	s_add_u32 s46, s46, 0x8000
	s_addc_u32 s47, s47, 0
	v_readlane_b32 s4, v253, 40
	v_readlane_b32 s5, v253, 41
	s_lshl_b32 s0, s29, 6
	s_add_u32 s28, s4, s0
	s_mov_b32 s7, s29
	s_addc_u32 s29, s5, 0
	global_load_dwordx4 v[56:59], v33, s[28:29]
	global_load_dwordx4 v[60:63], v33, s[28:29] offset:64
	global_load_dwordx4 v[64:67], v33, s[28:29] offset:128
	global_load_dwordx4 v[68:71], v33, s[28:29] offset:192
	global_load_dwordx4 v[72:75], v33, s[28:29] offset:256
	global_load_dwordx4 v[76:79], v33, s[28:29] offset:320
	global_load_dwordx4 v[80:83], v33, s[28:29] offset:384
	global_load_dwordx4 v[84:87], v33, s[28:29] offset:448
	v_readlane_b32 s4, v253, 11
	v_readlane_b32 s5, v253, 12
	s_add_u32 s4, s4, 0x1d302200
	s_addc_u32 s5, s5, 0
	s_add_i32 s30, s7, s22
	s_mul_i32 s30, s30, 0x3400
	s_add_u32 s30, s4, s30
	s_addc_u32 s31, s5, 0
	global_load_dwordx4 v[40:43], v35, s[30:31]
	global_load_dwordx4 v[44:47], v35, s[30:31] offset:1024
	global_load_dwordx4 v[48:51], v35, s[30:31] offset:2048
	global_load_dwordx4 v[52:55], v35, s[30:31] offset:3072
.Lsel_nopfA:
	s_cmp_gt_i32 s38, 3
	s_cbranch_scc1 .Lsel_big
	s_cmp_gt_i32 s38, -1
	s_cselect_b32 s4, 0, -1
	v_mov_b32_e32 v23, v34
	v_or_b32_e32 v23, s4, v23
	global_store_dword v28, v23, s[2:3]
	s_cmp_gt_i32 s38, 0
	s_cselect_b32 s4, 0, -1
	v_or_b32_e32 v23, 64, v34
	v_or_b32_e32 v23, s4, v23
	global_store_dword v28, v23, s[2:3] offset:256
	s_cmp_gt_i32 s38, 1
	s_cselect_b32 s4, 0, -1
	v_or_b32_e32 v23, 128, v34
	v_or_b32_e32 v23, s4, v23
	global_store_dword v28, v23, s[2:3] offset:512
	s_cmp_gt_i32 s38, 2
	s_cselect_b32 s4, 0, -1
	v_or_b32_e32 v23, 192, v34
	v_or_b32_e32 v23, s4, v23
	global_store_dword v28, v23, s[2:3] offset:768
	s_branch .Lsel_end
.Lsel_big:
	s_mov_b32 s28, 0x80000000
	s_lshl_b32 s27, s22, 10
	s_add_i32 s27, s27, 0x20000
	s_lshl_b32 s4, s22, 14
	v_lshl_add_u32 v22, v34, 2, s4
	v_mov_b32_e32 v4, 1
	v_mov_b32_e32 v24, 0
	v_mov_b32_e32 v25, 0
	v_mov_b32_e32 v26, 0
	v_mov_b32_e32 v27, 0
	v_lshlrev_b32_e32 v6, 4, v34
	v_sub_u32_e32 v7, 0x3f0, v6
	v_add_u32_e32 v6, s27, v6
	v_add_u32_e32 v7, s27, v7
	v_mov_b32_e32 v5, s27
	ds_write_b128 v6, v[24:27]
	ds_read_b32 v88, v22
	ds_read_b32 v89, v22 offset:256
	ds_read_b32 v90, v22 offset:512
	ds_read_b32 v91, v22 offset:768
	ds_read_b32 v92, v22 offset:1024
	ds_read_b32 v93, v22 offset:1280
	ds_read_b32 v94, v22 offset:1536
	ds_read_b32 v95, v22 offset:1792
	s_waitcnt lgkmcnt(0)
	v_cvt_f16_f32_sdwa v88, v88 dst_sel:WORD_1 dst_unused:UNUSED_PAD src0_sel:DWORD
	v_cvt_f16_f32_sdwa v89, v89 dst_sel:WORD_1 dst_unused:UNUSED_PAD src0_sel:DWORD
	s_nop 0
	v_ashrrev_i32_e32 v0, 31, v88
	v_ashrrev_i32_e32 v1, 31, v89
	v_bitop3_b32 v88, v88, v0, s28 bitop3:0x1e
	v_bitop3_b32 v89, v89, v1, s28 bitop3:0x1e
	v_cvt_f16_f32_sdwa v90, v90 dst_sel:WORD_1 dst_unused:UNUSED_PAD src0_sel:DWORD
	v_cvt_f16_f32_sdwa v91, v91 dst_sel:WORD_1 dst_unused:UNUSED_PAD src0_sel:DWORD
	s_nop 0
	v_ashrrev_i32_e32 v0, 31, v90
	v_ashrrev_i32_e32 v1, 31, v91
	v_bitop3_b32 v90, v90, v0, s28 bitop3:0x1e
	v_bitop3_b32 v91, v91, v1, s28 bitop3:0x1e
	v_cvt_f16_f32_sdwa v92, v92 dst_sel:WORD_1 dst_unused:UNUSED_PAD src0_sel:DWORD
	v_cvt_f16_f32_sdwa v93, v93 dst_sel:WORD_1 dst_unused:UNUSED_PAD src0_sel:DWORD
	s_nop 0
	v_ashrrev_i32_e32 v0, 31, v92
	v_ashrrev_i32_e32 v1, 31, v93
	v_bitop3_b32 v92, v92, v0, s28 bitop3:0x1e
	v_bitop3_b32 v93, v93, v1, s28 bitop3:0x1e
	v_cvt_f16_f32_sdwa v94, v94 dst_sel:WORD_1 dst_unused:UNUSED_PAD src0_sel:DWORD
	v_cvt_f16_f32_sdwa v95, v95 dst_sel:WORD_1 dst_unused:UNUSED_PAD src0_sel:DWORD
	s_nop 0
	v_ashrrev_i32_e32 v0, 31, v94
	v_ashrrev_i32_e32 v1, 31, v95
	v_bitop3_b32 v94, v94, v0, s28 bitop3:0x1e
	v_bitop3_b32 v95, v95, v1, s28 bitop3:0x1e
	ds_read_b32 v96, v22 offset:2048
	ds_read_b32 v97, v22 offset:2304
	ds_read_b32 v98, v22 offset:2560
	ds_read_b32 v99, v22 offset:2816
	ds_read_b32 v100, v22 offset:3072
	ds_read_b32 v101, v22 offset:3328
	ds_read_b32 v102, v22 offset:3584
	ds_read_b32 v103, v22 offset:3840
	s_cmp_gt_i32 s38, 6
	s_cbranch_scc1 .Lsel_kb_full0
	s_cmp_gt_i32 s38, 0
	s_cselect_b32 s4, -1, 0
	v_and_b32_e32 v89, s4, v89
	s_cmp_gt_i32 s38, 1
	s_cselect_b32 s4, -1, 0
	v_and_b32_e32 v90, s4, v90
	s_cmp_gt_i32 s38, 2
	s_cselect_b32 s4, -1, 0
	v_and_b32_e32 v91, s4, v91
	s_cmp_gt_i32 s38, 3
	s_cselect_b32 s4, -1, 0
	v_and_b32_e32 v92, s4, v92
	s_cmp_gt_i32 s38, 4
	s_cselect_b32 s4, -1, 0
	v_and_b32_e32 v93, s4, v93
	s_cmp_gt_i32 s38, 5
	s_cselect_b32 s4, -1, 0
	v_and_b32_e32 v94, s4, v94
	s_cmp_gt_i32 s38, 6
	s_cselect_b32 s4, -1, 0
	v_and_b32_e32 v95, s4, v95
	v_bfe_u32 v2, v88, 24, 8
	v_lshl_add_u32 v2, v2, 2, v5
	ds_add_u32 v2, v4
	v_bfe_u32 v3, v89, 24, 8
	v_lshl_add_u32 v3, v3, 2, v5
	ds_add_u32 v3, v4
	v_bfe_u32 v2, v90, 24, 8
	v_lshl_add_u32 v2, v2, 2, v5
	ds_add_u32 v2, v4
	v_bfe_u32 v3, v91, 24, 8
	v_lshl_add_u32 v3, v3, 2, v5
	ds_add_u32 v3, v4
	v_bfe_u32 v2, v92, 24, 8
	v_lshl_add_u32 v2, v2, 2, v5
	ds_add_u32 v2, v4
	v_bfe_u32 v3, v93, 24, 8
	v_lshl_add_u32 v3, v3, 2, v5
	ds_add_u32 v3, v4
	v_bfe_u32 v2, v94, 24, 8
	v_lshl_add_u32 v2, v2, 2, v5
	ds_add_u32 v2, v4
	v_bfe_u32 v3, v95, 24, 8
	v_lshl_add_u32 v3, v3, 2, v5
	ds_add_u32 v3, v4
	s_branch .Lsel_kb_done
.Lsel_kb_full0:
	v_bfe_u32 v2, v88, 24, 8
	v_lshl_add_u32 v2, v2, 2, v5
	ds_add_u32 v2, v4
	v_bfe_u32 v3, v89, 24, 8
	v_lshl_add_u32 v3, v3, 2, v5
	ds_add_u32 v3, v4
	v_bfe_u32 v2, v90, 24, 8
	v_lshl_add_u32 v2, v2, 2, v5
	ds_add_u32 v2, v4
	v_bfe_u32 v3, v91, 24, 8
	v_lshl_add_u32 v3, v3, 2, v5
	ds_add_u32 v3, v4
	v_bfe_u32 v2, v92, 24, 8
	v_lshl_add_u32 v2, v2, 2, v5
	ds_add_u32 v2, v4
	v_bfe_u32 v3, v93, 24, 8
	v_lshl_add_u32 v3, v3, 2, v5
	ds_add_u32 v3, v4
	v_bfe_u32 v2, v94, 24, 8
	v_lshl_add_u32 v2, v2, 2, v5
	ds_add_u32 v2, v4
	v_bfe_u32 v3, v95, 24, 8
	v_lshl_add_u32 v3, v3, 2, v5
	ds_add_u32 v3, v4
	s_cmp_lt_i32 s38, 8
	s_cbranch_scc1 .Lsel_kb_done
	s_waitcnt lgkmcnt(8)
	v_cvt_f16_f32_sdwa v96, v96 dst_sel:WORD_1 dst_unused:UNUSED_PAD src0_sel:DWORD
	v_cvt_f16_f32_sdwa v97, v97 dst_sel:WORD_1 dst_unused:UNUSED_PAD src0_sel:DWORD
	s_nop 0
	v_ashrrev_i32_e32 v0, 31, v96
	v_ashrrev_i32_e32 v1, 31, v97
	v_bitop3_b32 v96, v96, v0, s28 bitop3:0x1e
	v_bitop3_b32 v97, v97, v1, s28 bitop3:0x1e
	v_cvt_f16_f32_sdwa v98, v98 dst_sel:WORD_1 dst_unused:UNUSED_PAD src0_sel:DWORD
	v_cvt_f16_f32_sdwa v99, v99 dst_sel:WORD_1 dst_unused:UNUSED_PAD src0_sel:DWORD
	s_nop 0
	v_ashrrev_i32_e32 v0, 31, v98
	v_ashrrev_i32_e32 v1, 31, v99
	v_bitop3_b32 v98, v98, v0, s28 bitop3:0x1e
	v_bitop3_b32 v99, v99, v1, s28 bitop3:0x1e
	v_cvt_f16_f32_sdwa v100, v100 dst_sel:WORD_1 dst_unused:UNUSED_PAD src0_sel:DWORD
	v_cvt_f16_f32_sdwa v101, v101 dst_sel:WORD_1 dst_unused:UNUSED_PAD src0_sel:DWORD
	s_nop 0
	v_ashrrev_i32_e32 v0, 31, v100
	v_ashrrev_i32_e32 v1, 31, v101
	v_bitop3_b32 v100, v100, v0, s28 bitop3:0x1e
	v_bitop3_b32 v101, v101, v1, s28 bitop3:0x1e
	v_cvt_f16_f32_sdwa v102, v102 dst_sel:WORD_1 dst_unused:UNUSED_PAD src0_sel:DWORD
	v_cvt_f16_f32_sdwa v103, v103 dst_sel:WORD_1 dst_unused:UNUSED_PAD src0_sel:DWORD
	s_nop 0
	v_ashrrev_i32_e32 v0, 31, v102
	v_ashrrev_i32_e32 v1, 31, v103
	v_bitop3_b32 v102, v102, v0, s28 bitop3:0x1e
	v_bitop3_b32 v103, v103, v1, s28 bitop3:0x1e
	ds_read_b32 v104, v22 offset:4096
	ds_read_b32 v105, v22 offset:4352
	ds_read_b32 v106, v22 offset:4608
	ds_read_b32 v107, v22 offset:4864
	ds_read_b32 v108, v22 offset:5120
	ds_read_b32 v109, v22 offset:5376
	ds_read_b32 v110, v22 offset:5632
	ds_read_b32 v111, v22 offset:5888
	s_cmp_gt_i32 s38, 14
	s_cbranch_scc1 .Lsel_kb_full1
	s_cmp_gt_i32 s38, 8
	s_cselect_b32 s4, -1, 0
	v_and_b32_e32 v97, s4, v97
	s_cmp_gt_i32 s38, 9
	s_cselect_b32 s4, -1, 0
	v_and_b32_e32 v98, s4, v98
	s_cmp_gt_i32 s38, 10
	s_cselect_b32 s4, -1, 0
	v_and_b32_e32 v99, s4, v99
	s_cmp_gt_i32 s38, 11
	s_cselect_b32 s4, -1, 0
	v_and_b32_e32 v100, s4, v100
	s_cmp_gt_i32 s38, 12
	s_cselect_b32 s4, -1, 0
	v_and_b32_e32 v101, s4, v101
	s_cmp_gt_i32 s38, 13
	s_cselect_b32 s4, -1, 0
	v_and_b32_e32 v102, s4, v102
	s_cmp_gt_i32 s38, 14
	s_cselect_b32 s4, -1, 0
	v_and_b32_e32 v103, s4, v103
	v_bfe_u32 v2, v96, 24, 8
	v_lshl_add_u32 v2, v2, 2, v5
	ds_add_u32 v2, v4
	v_bfe_u32 v3, v97, 24, 8
	v_lshl_add_u32 v3, v3, 2, v5
	ds_add_u32 v3, v4
	v_bfe_u32 v2, v98, 24, 8
	v_lshl_add_u32 v2, v2, 2, v5
	ds_add_u32 v2, v4
	v_bfe_u32 v3, v99, 24, 8
	v_lshl_add_u32 v3, v3, 2, v5
	ds_add_u32 v3, v4
	v_bfe_u32 v2, v100, 24, 8
	v_lshl_add_u32 v2, v2, 2, v5
	ds_add_u32 v2, v4
	v_bfe_u32 v3, v101, 24, 8
	v_lshl_add_u32 v3, v3, 2, v5
	ds_add_u32 v3, v4
	v_bfe_u32 v2, v102, 24, 8
	v_lshl_add_u32 v2, v2, 2, v5
	ds_add_u32 v2, v4
	v_bfe_u32 v3, v103, 24, 8
	v_lshl_add_u32 v3, v3, 2, v5
	ds_add_u32 v3, v4
	s_branch .Lsel_kb_done
.Lsel_kb_full1:
	v_bfe_u32 v2, v96, 24, 8
	v_lshl_add_u32 v2, v2, 2, v5
	ds_add_u32 v2, v4
	v_bfe_u32 v3, v97, 24, 8
	v_lshl_add_u32 v3, v3, 2, v5
	ds_add_u32 v3, v4
	v_bfe_u32 v2, v98, 24, 8
	v_lshl_add_u32 v2, v2, 2, v5
	ds_add_u32 v2, v4
	v_bfe_u32 v3, v99, 24, 8
	v_lshl_add_u32 v3, v3, 2, v5
	ds_add_u32 v3, v4
	v_bfe_u32 v2, v100, 24, 8
	v_lshl_add_u32 v2, v2, 2, v5
	ds_add_u32 v2, v4
	v_bfe_u32 v3, v101, 24, 8
	v_lshl_add_u32 v3, v3, 2, v5
	ds_add_u32 v3, v4
	v_bfe_u32 v2, v102, 24, 8
	v_lshl_add_u32 v2, v2, 2, v5
	ds_add_u32 v2, v4
	v_bfe_u32 v3, v103, 24, 8
	v_lshl_add_u32 v3, v3, 2, v5
	ds_add_u32 v3, v4
	s_cmp_lt_i32 s38, 16
	s_cbranch_scc1 .Lsel_kb_done
	s_waitcnt lgkmcnt(8)
	v_cvt_f16_f32_sdwa v104, v104 dst_sel:WORD_1 dst_unused:UNUSED_PAD src0_sel:DWORD
	v_cvt_f16_f32_sdwa v105, v105 dst_sel:WORD_1 dst_unused:UNUSED_PAD src0_sel:DWORD
	s_nop 0
	v_ashrrev_i32_e32 v0, 31, v104
	v_ashrrev_i32_e32 v1, 31, v105
	v_bitop3_b32 v104, v104, v0, s28 bitop3:0x1e
	v_bitop3_b32 v105, v105, v1, s28 bitop3:0x1e
	v_cvt_f16_f32_sdwa v106, v106 dst_sel:WORD_1 dst_unused:UNUSED_PAD src0_sel:DWORD
	v_cvt_f16_f32_sdwa v107, v107 dst_sel:WORD_1 dst_unused:UNUSED_PAD src0_sel:DWORD
	s_nop 0
	v_ashrrev_i32_e32 v0, 31, v106
	v_ashrrev_i32_e32 v1, 31, v107
	v_bitop3_b32 v106, v106, v0, s28 bitop3:0x1e
	v_bitop3_b32 v107, v107, v1, s28 bitop3:0x1e
	v_cvt_f16_f32_sdwa v108, v108 dst_sel:WORD_1 dst_unused:UNUSED_PAD src0_sel:DWORD
	v_cvt_f16_f32_sdwa v109, v109 dst_sel:WORD_1 dst_unused:UNUSED_PAD src0_sel:DWORD
	s_nop 0
	v_ashrrev_i32_e32 v0, 31, v108
	v_ashrrev_i32_e32 v1, 31, v109
	v_bitop3_b32 v108, v108, v0, s28 bitop3:0x1e
	v_bitop3_b32 v109, v109, v1, s28 bitop3:0x1e
	v_cvt_f16_f32_sdwa v110, v110 dst_sel:WORD_1 dst_unused:UNUSED_PAD src0_sel:DWORD
	v_cvt_f16_f32_sdwa v111, v111 dst_sel:WORD_1 dst_unused:UNUSED_PAD src0_sel:DWORD
	s_nop 0
	v_ashrrev_i32_e32 v0, 31, v110
	v_ashrrev_i32_e32 v1, 31, v111
	v_bitop3_b32 v110, v110, v0, s28 bitop3:0x1e
	v_bitop3_b32 v111, v111, v1, s28 bitop3:0x1e
	ds_read_b32 v112, v22 offset:6144
	ds_read_b32 v113, v22 offset:6400
	ds_read_b32 v114, v22 offset:6656
	ds_read_b32 v115, v22 offset:6912
	ds_read_b32 v116, v22 offset:7168
	ds_read_b32 v117, v22 offset:7424
	ds_read_b32 v118, v22 offset:7680
	ds_read_b32 v119, v22 offset:7936
	s_cmp_gt_i32 s38, 22
	s_cbranch_scc1 .Lsel_kb_full2
	s_cmp_gt_i32 s38, 16
	s_cselect_b32 s4, -1, 0
	v_and_b32_e32 v105, s4, v105
	s_cmp_gt_i32 s38, 17
	s_cselect_b32 s4, -1, 0
	v_and_b32_e32 v106, s4, v106
	s_cmp_gt_i32 s38, 18
	s_cselect_b32 s4, -1, 0
	v_and_b32_e32 v107, s4, v107
	s_cmp_gt_i32 s38, 19
	s_cselect_b32 s4, -1, 0
	v_and_b32_e32 v108, s4, v108
	s_cmp_gt_i32 s38, 20
	s_cselect_b32 s4, -1, 0
	v_and_b32_e32 v109, s4, v109
	s_cmp_gt_i32 s38, 21
	s_cselect_b32 s4, -1, 0
	v_and_b32_e32 v110, s4, v110
	s_cmp_gt_i32 s38, 22
	s_cselect_b32 s4, -1, 0
	v_and_b32_e32 v111, s4, v111
	v_bfe_u32 v2, v104, 24, 8
	v_lshl_add_u32 v2, v2, 2, v5
	ds_add_u32 v2, v4
	v_bfe_u32 v3, v105, 24, 8
	v_lshl_add_u32 v3, v3, 2, v5
	ds_add_u32 v3, v4
	v_bfe_u32 v2, v106, 24, 8
	v_lshl_add_u32 v2, v2, 2, v5
	ds_add_u32 v2, v4
	v_bfe_u32 v3, v107, 24, 8
	v_lshl_add_u32 v3, v3, 2, v5
	ds_add_u32 v3, v4
	v_bfe_u32 v2, v108, 24, 8
	v_lshl_add_u32 v2, v2, 2, v5
	ds_add_u32 v2, v4
	v_bfe_u32 v3, v109, 24, 8
	v_lshl_add_u32 v3, v3, 2, v5
	ds_add_u32 v3, v4
	v_bfe_u32 v2, v110, 24, 8
	v_lshl_add_u32 v2, v2, 2, v5
	ds_add_u32 v2, v4
	v_bfe_u32 v3, v111, 24, 8
	v_lshl_add_u32 v3, v3, 2, v5
	ds_add_u32 v3, v4
	s_branch .Lsel_kb_done
.Lsel_kb_full2:
	v_bfe_u32 v2, v104, 24, 8
	v_lshl_add_u32 v2, v2, 2, v5
	ds_add_u32 v2, v4
	v_bfe_u32 v3, v105, 24, 8
	v_lshl_add_u32 v3, v3, 2, v5
	ds_add_u32 v3, v4
	v_bfe_u32 v2, v106, 24, 8
	v_lshl_add_u32 v2, v2, 2, v5
	ds_add_u32 v2, v4
	v_bfe_u32 v3, v107, 24, 8
	v_lshl_add_u32 v3, v3, 2, v5
	ds_add_u32 v3, v4
	v_bfe_u32 v2, v108, 24, 8
	v_lshl_add_u32 v2, v2, 2, v5
	ds_add_u32 v2, v4
	v_bfe_u32 v3, v109, 24, 8
	v_lshl_add_u32 v3, v3, 2, v5
	ds_add_u32 v3, v4
	v_bfe_u32 v2, v110, 24, 8
	v_lshl_add_u32 v2, v2, 2, v5
	ds_add_u32 v2, v4
	v_bfe_u32 v3, v111, 24, 8
	v_lshl_add_u32 v3, v3, 2, v5
	ds_add_u32 v3, v4
	s_cmp_lt_i32 s38, 24
	s_cbranch_scc1 .Lsel_kb_done
	s_waitcnt lgkmcnt(8)
	v_cvt_f16_f32_sdwa v112, v112 dst_sel:WORD_1 dst_unused:UNUSED_PAD src0_sel:DWORD
	v_cvt_f16_f32_sdwa v113, v113 dst_sel:WORD_1 dst_unused:UNUSED_PAD src0_sel:DWORD
	s_nop 0
	v_ashrrev_i32_e32 v0, 31, v112
	v_ashrrev_i32_e32 v1, 31, v113
	v_bitop3_b32 v112, v112, v0, s28 bitop3:0x1e
	v_bitop3_b32 v113, v113, v1, s28 bitop3:0x1e
	v_cvt_f16_f32_sdwa v114, v114 dst_sel:WORD_1 dst_unused:UNUSED_PAD src0_sel:DWORD
	v_cvt_f16_f32_sdwa v115, v115 dst_sel:WORD_1 dst_unused:UNUSED_PAD src0_sel:DWORD
	s_nop 0
	v_ashrrev_i32_e32 v0, 31, v114
	v_ashrrev_i32_e32 v1, 31, v115
	v_bitop3_b32 v114, v114, v0, s28 bitop3:0x1e
	v_bitop3_b32 v115, v115, v1, s28 bitop3:0x1e
	v_cvt_f16_f32_sdwa v116, v116 dst_sel:WORD_1 dst_unused:UNUSED_PAD src0_sel:DWORD
	v_cvt_f16_f32_sdwa v117, v117 dst_sel:WORD_1 dst_unused:UNUSED_PAD src0_sel:DWORD
	s_nop 0
	v_ashrrev_i32_e32 v0, 31, v116
	v_ashrrev_i32_e32 v1, 31, v117
	v_bitop3_b32 v116, v116, v0, s28 bitop3:0x1e
	v_bitop3_b32 v117, v117, v1, s28 bitop3:0x1e
	v_cvt_f16_f32_sdwa v118, v118 dst_sel:WORD_1 dst_unused:UNUSED_PAD src0_sel:DWORD
	v_cvt_f16_f32_sdwa v119, v119 dst_sel:WORD_1 dst_unused:UNUSED_PAD src0_sel:DWORD
	s_nop 0
	v_ashrrev_i32_e32 v0, 31, v118
	v_ashrrev_i32_e32 v1, 31, v119
	v_bitop3_b32 v118, v118, v0, s28 bitop3:0x1e
	v_bitop3_b32 v119, v119, v1, s28 bitop3:0x1e
	ds_read_b32 v120, v22 offset:8192
	ds_read_b32 v121, v22 offset:8448
	ds_read_b32 v122, v22 offset:8704
	ds_read_b32 v123, v22 offset:8960
	ds_read_b32 v124, v22 offset:9216
	ds_read_b32 v125, v22 offset:9472
	ds_read_b32 v126, v22 offset:9728
	ds_read_b32 v127, v22 offset:9984
	s_cmp_gt_i32 s38, 30
	s_cbranch_scc1 .Lsel_kb_full3
	s_cmp_gt_i32 s38, 24
	s_cselect_b32 s4, -1, 0
	v_and_b32_e32 v113, s4, v113
	s_cmp_gt_i32 s38, 25
	s_cselect_b32 s4, -1, 0
	v_and_b32_e32 v114, s4, v114
	s_cmp_gt_i32 s38, 26
	s_cselect_b32 s4, -1, 0
	v_and_b32_e32 v115, s4, v115
	s_cmp_gt_i32 s38, 27
	s_cselect_b32 s4, -1, 0
	v_and_b32_e32 v116, s4, v116
	s_cmp_gt_i32 s38, 28
	s_cselect_b32 s4, -1, 0
	v_and_b32_e32 v117, s4, v117
	s_cmp_gt_i32 s38, 29
	s_cselect_b32 s4, -1, 0
	v_and_b32_e32 v118, s4, v118
	s_cmp_gt_i32 s38, 30
	s_cselect_b32 s4, -1, 0
	v_and_b32_e32 v119, s4, v119
	v_bfe_u32 v2, v112, 24, 8
	v_lshl_add_u32 v2, v2, 2, v5
	ds_add_u32 v2, v4
	v_bfe_u32 v3, v113, 24, 8
	v_lshl_add_u32 v3, v3, 2, v5
	ds_add_u32 v3, v4
	v_bfe_u32 v2, v114, 24, 8
	v_lshl_add_u32 v2, v2, 2, v5
	ds_add_u32 v2, v4
	v_bfe_u32 v3, v115, 24, 8
	v_lshl_add_u32 v3, v3, 2, v5
	ds_add_u32 v3, v4
	v_bfe_u32 v2, v116, 24, 8
	v_lshl_add_u32 v2, v2, 2, v5
	ds_add_u32 v2, v4
	v_bfe_u32 v3, v117, 24, 8
	v_lshl_add_u32 v3, v3, 2, v5
	ds_add_u32 v3, v4
	v_bfe_u32 v2, v118, 24, 8
	v_lshl_add_u32 v2, v2, 2, v5
	ds_add_u32 v2, v4
	v_bfe_u32 v3, v119, 24, 8
	v_lshl_add_u32 v3, v3, 2, v5
	ds_add_u32 v3, v4
	s_branch .Lsel_kb_done
.Lsel_kb_full3:
	v_bfe_u32 v2, v112, 24, 8
	v_lshl_add_u32 v2, v2, 2, v5
	ds_add_u32 v2, v4
	v_bfe_u32 v3, v113, 24, 8
	v_lshl_add_u32 v3, v3, 2, v5
	ds_add_u32 v3, v4
	v_bfe_u32 v2, v114, 24, 8
	v_lshl_add_u32 v2, v2, 2, v5
	ds_add_u32 v2, v4
	v_bfe_u32 v3, v115, 24, 8
	v_lshl_add_u32 v3, v3, 2, v5
	ds_add_u32 v3, v4
	v_bfe_u32 v2, v116, 24, 8
	v_lshl_add_u32 v2, v2, 2, v5
	ds_add_u32 v2, v4
	v_bfe_u32 v3, v117, 24, 8
	v_lshl_add_u32 v3, v3, 2, v5
	ds_add_u32 v3, v4
	v_bfe_u32 v2, v118, 24, 8
	v_lshl_add_u32 v2, v2, 2, v5
	ds_add_u32 v2, v4
	v_bfe_u32 v3, v119, 24, 8
	v_lshl_add_u32 v3, v3, 2, v5
	ds_add_u32 v3, v4
	s_cmp_lt_i32 s38, 32
	s_cbranch_scc1 .Lsel_kb_done
	s_waitcnt lgkmcnt(8)
	v_cvt_f16_f32_sdwa v120, v120 dst_sel:WORD_1 dst_unused:UNUSED_PAD src0_sel:DWORD
	v_cvt_f16_f32_sdwa v121, v121 dst_sel:WORD_1 dst_unused:UNUSED_PAD src0_sel:DWORD
	s_nop 0
	v_ashrrev_i32_e32 v0, 31, v120
	v_ashrrev_i32_e32 v1, 31, v121
	v_bitop3_b32 v120, v120, v0, s28 bitop3:0x1e
	v_bitop3_b32 v121, v121, v1, s28 bitop3:0x1e
	v_cvt_f16_f32_sdwa v122, v122 dst_sel:WORD_1 dst_unused:UNUSED_PAD src0_sel:DWORD
	v_cvt_f16_f32_sdwa v123, v123 dst_sel:WORD_1 dst_unused:UNUSED_PAD src0_sel:DWORD
	s_nop 0
	v_ashrrev_i32_e32 v0, 31, v122
	v_ashrrev_i32_e32 v1, 31, v123
	v_bitop3_b32 v122, v122, v0, s28 bitop3:0x1e
	v_bitop3_b32 v123, v123, v1, s28 bitop3:0x1e
	v_cvt_f16_f32_sdwa v124, v124 dst_sel:WORD_1 dst_unused:UNUSED_PAD src0_sel:DWORD
	v_cvt_f16_f32_sdwa v125, v125 dst_sel:WORD_1 dst_unused:UNUSED_PAD src0_sel:DWORD
	s_nop 0
	v_ashrrev_i32_e32 v0, 31, v124
	v_ashrrev_i32_e32 v1, 31, v125
	v_bitop3_b32 v124, v124, v0, s28 bitop3:0x1e
	v_bitop3_b32 v125, v125, v1, s28 bitop3:0x1e
	v_cvt_f16_f32_sdwa v126, v126 dst_sel:WORD_1 dst_unused:UNUSED_PAD src0_sel:DWORD
	v_cvt_f16_f32_sdwa v127, v127 dst_sel:WORD_1 dst_unused:UNUSED_PAD src0_sel:DWORD
	s_nop 0
	v_ashrrev_i32_e32 v0, 31, v126
	v_ashrrev_i32_e32 v1, 31, v127
	v_bitop3_b32 v126, v126, v0, s28 bitop3:0x1e
	v_bitop3_b32 v127, v127, v1, s28 bitop3:0x1e
	ds_read_b32 v128, v22 offset:10240
	ds_read_b32 v129, v22 offset:10496
	ds_read_b32 v130, v22 offset:10752
	ds_read_b32 v131, v22 offset:11008
	ds_read_b32 v132, v22 offset:11264
	ds_read_b32 v133, v22 offset:11520
	ds_read_b32 v134, v22 offset:11776
	ds_read_b32 v135, v22 offset:12032
	s_cmp_gt_i32 s38, 38
	s_cbranch_scc1 .Lsel_kb_full4
	s_cmp_gt_i32 s38, 32
	s_cselect_b32 s4, -1, 0
	v_and_b32_e32 v121, s4, v121
	s_cmp_gt_i32 s38, 33
	s_cselect_b32 s4, -1, 0
	v_and_b32_e32 v122, s4, v122
	s_cmp_gt_i32 s38, 34
	s_cselect_b32 s4, -1, 0
	v_and_b32_e32 v123, s4, v123
	s_cmp_gt_i32 s38, 35
	s_cselect_b32 s4, -1, 0
	v_and_b32_e32 v124, s4, v124
	s_cmp_gt_i32 s38, 36
	s_cselect_b32 s4, -1, 0
	v_and_b32_e32 v125, s4, v125
	s_cmp_gt_i32 s38, 37
	s_cselect_b32 s4, -1, 0
	v_and_b32_e32 v126, s4, v126
	s_cmp_gt_i32 s38, 38
	s_cselect_b32 s4, -1, 0
	v_and_b32_e32 v127, s4, v127
	v_bfe_u32 v2, v120, 24, 8
	v_lshl_add_u32 v2, v2, 2, v5
	ds_add_u32 v2, v4
	v_bfe_u32 v3, v121, 24, 8
	v_lshl_add_u32 v3, v3, 2, v5
	ds_add_u32 v3, v4
	v_bfe_u32 v2, v122, 24, 8
	v_lshl_add_u32 v2, v2, 2, v5
	ds_add_u32 v2, v4
	v_bfe_u32 v3, v123, 24, 8
	v_lshl_add_u32 v3, v3, 2, v5
	ds_add_u32 v3, v4
	v_bfe_u32 v2, v124, 24, 8
	v_lshl_add_u32 v2, v2, 2, v5
	ds_add_u32 v2, v4
	v_bfe_u32 v3, v125, 24, 8
	v_lshl_add_u32 v3, v3, 2, v5
	ds_add_u32 v3, v4
	v_bfe_u32 v2, v126, 24, 8
	v_lshl_add_u32 v2, v2, 2, v5
	ds_add_u32 v2, v4
	v_bfe_u32 v3, v127, 24, 8
	v_lshl_add_u32 v3, v3, 2, v5
	ds_add_u32 v3, v4
	s_branch .Lsel_kb_done
.Lsel_kb_full4:
	v_bfe_u32 v2, v120, 24, 8
	v_lshl_add_u32 v2, v2, 2, v5
	ds_add_u32 v2, v4
	v_bfe_u32 v3, v121, 24, 8
	v_lshl_add_u32 v3, v3, 2, v5
	ds_add_u32 v3, v4
	v_bfe_u32 v2, v122, 24, 8
	v_lshl_add_u32 v2, v2, 2, v5
	ds_add_u32 v2, v4
	v_bfe_u32 v3, v123, 24, 8
	v_lshl_add_u32 v3, v3, 2, v5
	ds_add_u32 v3, v4
	v_bfe_u32 v2, v124, 24, 8
	v_lshl_add_u32 v2, v2, 2, v5
	ds_add_u32 v2, v4
	v_bfe_u32 v3, v125, 24, 8
	v_lshl_add_u32 v3, v3, 2, v5
	ds_add_u32 v3, v4
	v_bfe_u32 v2, v126, 24, 8
	v_lshl_add_u32 v2, v2, 2, v5
	ds_add_u32 v2, v4
	v_bfe_u32 v3, v127, 24, 8
	v_lshl_add_u32 v3, v3, 2, v5
	ds_add_u32 v3, v4
	s_cmp_lt_i32 s38, 40
	s_cbranch_scc1 .Lsel_kb_done
	s_waitcnt lgkmcnt(8)
	v_cvt_f16_f32_sdwa v128, v128 dst_sel:WORD_1 dst_unused:UNUSED_PAD src0_sel:DWORD
	v_cvt_f16_f32_sdwa v129, v129 dst_sel:WORD_1 dst_unused:UNUSED_PAD src0_sel:DWORD
	s_nop 0
	v_ashrrev_i32_e32 v0, 31, v128
	v_ashrrev_i32_e32 v1, 31, v129
	v_bitop3_b32 v128, v128, v0, s28 bitop3:0x1e
	v_bitop3_b32 v129, v129, v1, s28 bitop3:0x1e
	v_cvt_f16_f32_sdwa v130, v130 dst_sel:WORD_1 dst_unused:UNUSED_PAD src0_sel:DWORD
	v_cvt_f16_f32_sdwa v131, v131 dst_sel:WORD_1 dst_unused:UNUSED_PAD src0_sel:DWORD
	s_nop 0
	v_ashrrev_i32_e32 v0, 31, v130
	v_ashrrev_i32_e32 v1, 31, v131
	v_bitop3_b32 v130, v130, v0, s28 bitop3:0x1e
	v_bitop3_b32 v131, v131, v1, s28 bitop3:0x1e
	v_cvt_f16_f32_sdwa v132, v132 dst_sel:WORD_1 dst_unused:UNUSED_PAD src0_sel:DWORD
	v_cvt_f16_f32_sdwa v133, v133 dst_sel:WORD_1 dst_unused:UNUSED_PAD src0_sel:DWORD
	s_nop 0
	v_ashrrev_i32_e32 v0, 31, v132
	v_ashrrev_i32_e32 v1, 31, v133
	v_bitop3_b32 v132, v132, v0, s28 bitop3:0x1e
	v_bitop3_b32 v133, v133, v1, s28 bitop3:0x1e
	v_cvt_f16_f32_sdwa v134, v134 dst_sel:WORD_1 dst_unused:UNUSED_PAD src0_sel:DWORD
	v_cvt_f16_f32_sdwa v135, v135 dst_sel:WORD_1 dst_unused:UNUSED_PAD src0_sel:DWORD
	s_nop 0
	v_ashrrev_i32_e32 v0, 31, v134
	v_ashrrev_i32_e32 v1, 31, v135
	v_bitop3_b32 v134, v134, v0, s28 bitop3:0x1e
	v_bitop3_b32 v135, v135, v1, s28 bitop3:0x1e
	ds_read_b32 v136, v22 offset:12288
	ds_read_b32 v137, v22 offset:12544
	ds_read_b32 v138, v22 offset:12800
	ds_read_b32 v139, v22 offset:13056
	ds_read_b32 v140, v22 offset:13312
	ds_read_b32 v141, v22 offset:13568
	ds_read_b32 v142, v22 offset:13824
	ds_read_b32 v143, v22 offset:14080
	s_cmp_gt_i32 s38, 46
	s_cbranch_scc1 .Lsel_kb_full5
	s_cmp_gt_i32 s38, 40
	s_cselect_b32 s4, -1, 0
	v_and_b32_e32 v129, s4, v129
	s_cmp_gt_i32 s38, 41
	s_cselect_b32 s4, -1, 0
	v_and_b32_e32 v130, s4, v130
	s_cmp_gt_i32 s38, 42
	s_cselect_b32 s4, -1, 0
	v_and_b32_e32 v131, s4, v131
	s_cmp_gt_i32 s38, 43
	s_cselect_b32 s4, -1, 0
	v_and_b32_e32 v132, s4, v132
	s_cmp_gt_i32 s38, 44
	s_cselect_b32 s4, -1, 0
	v_and_b32_e32 v133, s4, v133
	s_cmp_gt_i32 s38, 45
	s_cselect_b32 s4, -1, 0
	v_and_b32_e32 v134, s4, v134
	s_cmp_gt_i32 s38, 46
	s_cselect_b32 s4, -1, 0
	v_and_b32_e32 v135, s4, v135
	v_bfe_u32 v2, v128, 24, 8
	v_lshl_add_u32 v2, v2, 2, v5
	ds_add_u32 v2, v4
	v_bfe_u32 v3, v129, 24, 8
	v_lshl_add_u32 v3, v3, 2, v5
	ds_add_u32 v3, v4
	v_bfe_u32 v2, v130, 24, 8
	v_lshl_add_u32 v2, v2, 2, v5
	ds_add_u32 v2, v4
	v_bfe_u32 v3, v131, 24, 8
	v_lshl_add_u32 v3, v3, 2, v5
	ds_add_u32 v3, v4
	v_bfe_u32 v2, v132, 24, 8
	v_lshl_add_u32 v2, v2, 2, v5
	ds_add_u32 v2, v4
	v_bfe_u32 v3, v133, 24, 8
	v_lshl_add_u32 v3, v3, 2, v5
	ds_add_u32 v3, v4
	v_bfe_u32 v2, v134, 24, 8
	v_lshl_add_u32 v2, v2, 2, v5
	ds_add_u32 v2, v4
	v_bfe_u32 v3, v135, 24, 8
	v_lshl_add_u32 v3, v3, 2, v5
	ds_add_u32 v3, v4
	s_branch .Lsel_kb_done
.Lsel_kb_full5:
	v_bfe_u32 v2, v128, 24, 8
	v_lshl_add_u32 v2, v2, 2, v5
	ds_add_u32 v2, v4
	v_bfe_u32 v3, v129, 24, 8
	v_lshl_add_u32 v3, v3, 2, v5
	ds_add_u32 v3, v4
	v_bfe_u32 v2, v130, 24, 8
	v_lshl_add_u32 v2, v2, 2, v5
	ds_add_u32 v2, v4
	v_bfe_u32 v3, v131, 24, 8
	v_lshl_add_u32 v3, v3, 2, v5
	ds_add_u32 v3, v4
	v_bfe_u32 v2, v132, 24, 8
	v_lshl_add_u32 v2, v2, 2, v5
	ds_add_u32 v2, v4
	v_bfe_u32 v3, v133, 24, 8
	v_lshl_add_u32 v3, v3, 2, v5
	ds_add_u32 v3, v4
	v_bfe_u32 v2, v134, 24, 8
	v_lshl_add_u32 v2, v2, 2, v5
	ds_add_u32 v2, v4
	v_bfe_u32 v3, v135, 24, 8
	v_lshl_add_u32 v3, v3, 2, v5
	ds_add_u32 v3, v4
	s_cmp_lt_i32 s38, 48
	s_cbranch_scc1 .Lsel_kb_done
	s_waitcnt lgkmcnt(8)
	v_cvt_f16_f32_sdwa v136, v136 dst_sel:WORD_1 dst_unused:UNUSED_PAD src0_sel:DWORD
	v_cvt_f16_f32_sdwa v137, v137 dst_sel:WORD_1 dst_unused:UNUSED_PAD src0_sel:DWORD
	s_nop 0
	v_ashrrev_i32_e32 v0, 31, v136
	v_ashrrev_i32_e32 v1, 31, v137
	v_bitop3_b32 v136, v136, v0, s28 bitop3:0x1e
	v_bitop3_b32 v137, v137, v1, s28 bitop3:0x1e
	v_cvt_f16_f32_sdwa v138, v138 dst_sel:WORD_1 dst_unused:UNUSED_PAD src0_sel:DWORD
	v_cvt_f16_f32_sdwa v139, v139 dst_sel:WORD_1 dst_unused:UNUSED_PAD src0_sel:DWORD
	s_nop 0
	v_ashrrev_i32_e32 v0, 31, v138
	v_ashrrev_i32_e32 v1, 31, v139
	v_bitop3_b32 v138, v138, v0, s28 bitop3:0x1e
	v_bitop3_b32 v139, v139, v1, s28 bitop3:0x1e
	v_cvt_f16_f32_sdwa v140, v140 dst_sel:WORD_1 dst_unused:UNUSED_PAD src0_sel:DWORD
	v_cvt_f16_f32_sdwa v141, v141 dst_sel:WORD_1 dst_unused:UNUSED_PAD src0_sel:DWORD
	s_nop 0
	v_ashrrev_i32_e32 v0, 31, v140
	v_ashrrev_i32_e32 v1, 31, v141
	v_bitop3_b32 v140, v140, v0, s28 bitop3:0x1e
	v_bitop3_b32 v141, v141, v1, s28 bitop3:0x1e
	v_cvt_f16_f32_sdwa v142, v142 dst_sel:WORD_1 dst_unused:UNUSED_PAD src0_sel:DWORD
	v_cvt_f16_f32_sdwa v143, v143 dst_sel:WORD_1 dst_unused:UNUSED_PAD src0_sel:DWORD
	s_nop 0
	v_ashrrev_i32_e32 v0, 31, v142
	v_ashrrev_i32_e32 v1, 31, v143
	v_bitop3_b32 v142, v142, v0, s28 bitop3:0x1e
	v_bitop3_b32 v143, v143, v1, s28 bitop3:0x1e
	ds_read_b32 v144, v22 offset:14336
	ds_read_b32 v145, v22 offset:14592
	ds_read_b32 v146, v22 offset:14848
	ds_read_b32 v147, v22 offset:15104
	ds_read_b32 v148, v22 offset:15360
	ds_read_b32 v149, v22 offset:15616
	ds_read_b32 v150, v22 offset:15872
	ds_read_b32 v151, v22 offset:16128
	s_cmp_gt_i32 s38, 54
	s_cbranch_scc1 .Lsel_kb_full6
	s_cmp_gt_i32 s38, 48
	s_cselect_b32 s4, -1, 0
	v_and_b32_e32 v137, s4, v137
	s_cmp_gt_i32 s38, 49
	s_cselect_b32 s4, -1, 0
	v_and_b32_e32 v138, s4, v138
	s_cmp_gt_i32 s38, 50
	s_cselect_b32 s4, -1, 0
	v_and_b32_e32 v139, s4, v139
	s_cmp_gt_i32 s38, 51
	s_cselect_b32 s4, -1, 0
	v_and_b32_e32 v140, s4, v140
	s_cmp_gt_i32 s38, 52
	s_cselect_b32 s4, -1, 0
	v_and_b32_e32 v141, s4, v141
	s_cmp_gt_i32 s38, 53
	s_cselect_b32 s4, -1, 0
	v_and_b32_e32 v142, s4, v142
	s_cmp_gt_i32 s38, 54
	s_cselect_b32 s4, -1, 0
	v_and_b32_e32 v143, s4, v143
	v_bfe_u32 v2, v136, 24, 8
	v_lshl_add_u32 v2, v2, 2, v5
	ds_add_u32 v2, v4
	v_bfe_u32 v3, v137, 24, 8
	v_lshl_add_u32 v3, v3, 2, v5
	ds_add_u32 v3, v4
	v_bfe_u32 v2, v138, 24, 8
	v_lshl_add_u32 v2, v2, 2, v5
	ds_add_u32 v2, v4
	v_bfe_u32 v3, v139, 24, 8
	v_lshl_add_u32 v3, v3, 2, v5
	ds_add_u32 v3, v4
	v_bfe_u32 v2, v140, 24, 8
	v_lshl_add_u32 v2, v2, 2, v5
	ds_add_u32 v2, v4
	v_bfe_u32 v3, v141, 24, 8
	v_lshl_add_u32 v3, v3, 2, v5
	ds_add_u32 v3, v4
	v_bfe_u32 v2, v142, 24, 8
	v_lshl_add_u32 v2, v2, 2, v5
	ds_add_u32 v2, v4
	v_bfe_u32 v3, v143, 24, 8
	v_lshl_add_u32 v3, v3, 2, v5
	ds_add_u32 v3, v4
	s_branch .Lsel_kb_done
.Lsel_kb_full6:
	v_bfe_u32 v2, v136, 24, 8
	v_lshl_add_u32 v2, v2, 2, v5
	ds_add_u32 v2, v4
	v_bfe_u32 v3, v137, 24, 8
	v_lshl_add_u32 v3, v3, 2, v5
	ds_add_u32 v3, v4
	v_bfe_u32 v2, v138, 24, 8
	v_lshl_add_u32 v2, v2, 2, v5
	ds_add_u32 v2, v4
	v_bfe_u32 v3, v139, 24, 8
	v_lshl_add_u32 v3, v3, 2, v5
	ds_add_u32 v3, v4
	v_bfe_u32 v2, v140, 24, 8
	v_lshl_add_u32 v2, v2, 2, v5
	ds_add_u32 v2, v4
	v_bfe_u32 v3, v141, 24, 8
	v_lshl_add_u32 v3, v3, 2, v5
	ds_add_u32 v3, v4
	v_bfe_u32 v2, v142, 24, 8
	v_lshl_add_u32 v2, v2, 2, v5
	ds_add_u32 v2, v4
	v_bfe_u32 v3, v143, 24, 8
	v_lshl_add_u32 v3, v3, 2, v5
	ds_add_u32 v3, v4
	s_cmp_lt_i32 s38, 56
	s_cbranch_scc1 .Lsel_kb_done
	s_waitcnt lgkmcnt(8)
	v_cvt_f16_f32_sdwa v144, v144 dst_sel:WORD_1 dst_unused:UNUSED_PAD src0_sel:DWORD
	v_cvt_f16_f32_sdwa v145, v145 dst_sel:WORD_1 dst_unused:UNUSED_PAD src0_sel:DWORD
	s_nop 0
	v_ashrrev_i32_e32 v0, 31, v144
	v_ashrrev_i32_e32 v1, 31, v145
	v_bitop3_b32 v144, v144, v0, s28 bitop3:0x1e
	v_bitop3_b32 v145, v145, v1, s28 bitop3:0x1e
	v_cvt_f16_f32_sdwa v146, v146 dst_sel:WORD_1 dst_unused:UNUSED_PAD src0_sel:DWORD
	v_cvt_f16_f32_sdwa v147, v147 dst_sel:WORD_1 dst_unused:UNUSED_PAD src0_sel:DWORD
	s_nop 0
	v_ashrrev_i32_e32 v0, 31, v146
	v_ashrrev_i32_e32 v1, 31, v147
	v_bitop3_b32 v146, v146, v0, s28 bitop3:0x1e
	v_bitop3_b32 v147, v147, v1, s28 bitop3:0x1e
	v_cvt_f16_f32_sdwa v148, v148 dst_sel:WORD_1 dst_unused:UNUSED_PAD src0_sel:DWORD
	v_cvt_f16_f32_sdwa v149, v149 dst_sel:WORD_1 dst_unused:UNUSED_PAD src0_sel:DWORD
	s_nop 0
	v_ashrrev_i32_e32 v0, 31, v148
	v_ashrrev_i32_e32 v1, 31, v149
	v_bitop3_b32 v148, v148, v0, s28 bitop3:0x1e
	v_bitop3_b32 v149, v149, v1, s28 bitop3:0x1e
	v_cvt_f16_f32_sdwa v150, v150 dst_sel:WORD_1 dst_unused:UNUSED_PAD src0_sel:DWORD
	v_cvt_f16_f32_sdwa v151, v151 dst_sel:WORD_1 dst_unused:UNUSED_PAD src0_sel:DWORD
	s_nop 0
	v_ashrrev_i32_e32 v0, 31, v150
	v_ashrrev_i32_e32 v1, 31, v151
	v_bitop3_b32 v150, v150, v0, s28 bitop3:0x1e
	v_bitop3_b32 v151, v151, v1, s28 bitop3:0x1e
	s_cmp_gt_i32 s38, 62
	s_cbranch_scc1 .Lsel_kb_full7
	s_cmp_gt_i32 s38, 56
	s_cselect_b32 s4, -1, 0
	v_and_b32_e32 v145, s4, v145
	s_cmp_gt_i32 s38, 57
	s_cselect_b32 s4, -1, 0
	v_and_b32_e32 v146, s4, v146
	s_cmp_gt_i32 s38, 58
	s_cselect_b32 s4, -1, 0
	v_and_b32_e32 v147, s4, v147
	s_cmp_gt_i32 s38, 59
	s_cselect_b32 s4, -1, 0
	v_and_b32_e32 v148, s4, v148
	s_cmp_gt_i32 s38, 60
	s_cselect_b32 s4, -1, 0
	v_and_b32_e32 v149, s4, v149
	s_cmp_gt_i32 s38, 61
	s_cselect_b32 s4, -1, 0
	v_and_b32_e32 v150, s4, v150
	s_cmp_gt_i32 s38, 62
	s_cselect_b32 s4, -1, 0
	v_and_b32_e32 v151, s4, v151
	v_bfe_u32 v2, v144, 24, 8
	v_lshl_add_u32 v2, v2, 2, v5
	ds_add_u32 v2, v4
	v_bfe_u32 v3, v145, 24, 8
	v_lshl_add_u32 v3, v3, 2, v5
	ds_add_u32 v3, v4
	v_bfe_u32 v2, v146, 24, 8
	v_lshl_add_u32 v2, v2, 2, v5
	ds_add_u32 v2, v4
	v_bfe_u32 v3, v147, 24, 8
	v_lshl_add_u32 v3, v3, 2, v5
	ds_add_u32 v3, v4
	v_bfe_u32 v2, v148, 24, 8
	v_lshl_add_u32 v2, v2, 2, v5
	ds_add_u32 v2, v4
	v_bfe_u32 v3, v149, 24, 8
	v_lshl_add_u32 v3, v3, 2, v5
	ds_add_u32 v3, v4
	v_bfe_u32 v2, v150, 24, 8
	v_lshl_add_u32 v2, v2, 2, v5
	ds_add_u32 v2, v4
	v_bfe_u32 v3, v151, 24, 8
	v_lshl_add_u32 v3, v3, 2, v5
	ds_add_u32 v3, v4
	s_branch .Lsel_kb_done
.Lsel_kb_full7:
	v_bfe_u32 v2, v144, 24, 8
	v_lshl_add_u32 v2, v2, 2, v5
	ds_add_u32 v2, v4
	v_bfe_u32 v3, v145, 24, 8
	v_lshl_add_u32 v3, v3, 2, v5
	ds_add_u32 v3, v4
	v_bfe_u32 v2, v146, 24, 8
	v_lshl_add_u32 v2, v2, 2, v5
	ds_add_u32 v2, v4
	v_bfe_u32 v3, v147, 24, 8
	v_lshl_add_u32 v3, v3, 2, v5
	ds_add_u32 v3, v4
	v_bfe_u32 v2, v148, 24, 8
	v_lshl_add_u32 v2, v2, 2, v5
	ds_add_u32 v2, v4
	v_bfe_u32 v3, v149, 24, 8
	v_lshl_add_u32 v3, v3, 2, v5
	ds_add_u32 v3, v4
	v_bfe_u32 v2, v150, 24, 8
	v_lshl_add_u32 v2, v2, 2, v5
	ds_add_u32 v2, v4
	v_bfe_u32 v3, v151, 24, 8
	v_lshl_add_u32 v3, v3, 2, v5
	ds_add_u32 v3, v4
.Lsel_kb_done:
	s_movk_i32 s29, 0x100
	s_waitcnt lgkmcnt(0)
	ds_read_b128 v[8:11], v7
	s_waitcnt lgkmcnt(0)
	ds_write_b128 v6, v[24:27]
	v_add3_u32 v12, v8, v9, v10
	v_add_u32_e32 v12, v12, v11
	v_mov_b32_e32 v13, v12
	s_nop 1
	v_add_u32_dpp v13, v13, v13 row_shr:1 row_mask:0xf bank_mask:0xf
	s_nop 1
	v_add_u32_dpp v13, v13, v13 row_shr:2 row_mask:0xf bank_mask:0xf
	s_nop 1
	v_add_u32_dpp v13, v13, v13 row_shr:4 row_mask:0xf bank_mask:0xf
	s_nop 1
	v_add_u32_dpp v13, v13, v13 row_shr:8 row_mask:0xf bank_mask:0xf
	s_nop 1
	v_readlane_b32 s40, v13, 15
	v_readlane_b32 s41, v13, 31
	v_readlane_b32 s42, v13, 47
	s_add_i32 s41, s40, s41
	s_add_i32 s42, s41, s42
	s_mov_b32 exec_lo, 0xffff0000
	s_mov_b32 exec_hi, 0
	v_add_u32_e32 v13, s40, v13
	s_mov_b32 exec_lo, 0
	s_mov_b32 exec_hi, 0xffff
	v_add_u32_e32 v13, s41, v13
	s_mov_b32 exec_hi, 0xffff0000
	v_add_u32_e32 v13, s42, v13
	s_mov_b64 exec, -1
	v_sub_u32_e32 v14, v13, v12
	v_add_u32_e32 v15, v14, v11
	v_add_u32_e32 v16, v15, v10
	v_add_u32_e32 v17, v16, v9
	v_cmp_gt_u32_e32 vcc, s29, v14
	s_bcnt1_i32_b64 s30, vcc
	v_cmp_gt_u32_e32 vcc, s29, v15
	s_bcnt1_i32_b64 s4, vcc
	s_add_i32 s30, s30, s4
	v_cmp_gt_u32_e32 vcc, s29, v16
	s_bcnt1_i32_b64 s4, vcc
	s_add_i32 s30, s30, s4
	v_cmp_gt_u32_e32 vcc, s29, v17
	s_bcnt1_i32_b64 s4, vcc
	s_add_i32 s30, s30, s4
	s_add_i32 s30, s30, -1
	s_lshr_b32 s5, s30, 2
	s_and_b32 s6, s30, 3
	s_sub_i32 s34, 0xff, s30
	s_nop 3
	v_readlane_b32 s40, v14, s5
	v_readlane_b32 s41, v15, s5
	v_readlane_b32 s42, v16, s5
	v_readlane_b32 s43, v17, s5
	s_cmp_eq_u32 s6, 1
	s_cselect_b32 s40, s41, s40
	s_cmp_eq_u32 s6, 2
	s_cselect_b32 s40, s42, s40
	s_cmp_eq_u32 s6, 3
	s_cselect_b32 s40, s43, s40
	s_mov_b32 s35, s40
	s_sub_i32 s29, 0x100, s35
	s_lshl_b32 s36, s34, 24
	v_subrev_u32_e32 v2, s36, v88
	v_cmp_gt_u32_e32 vcc, 0x1000000, v2
	v_bfe_u32 v3, v2, 16, 8
	v_lshl_add_u32 v3, v3, 2, v5
	s_mov_b64 exec, vcc
	ds_add_u32 v3, v4
	s_mov_b64 exec, -1
	v_subrev_u32_e32 v2, s36, v89
	v_cmp_gt_u32_e32 vcc, 0x1000000, v2
	v_bfe_u32 v3, v2, 16, 8
	v_lshl_add_u32 v3, v3, 2, v5
	s_mov_b64 exec, vcc
	ds_add_u32 v3, v4
	s_mov_b64 exec, -1
	v_subrev_u32_e32 v2, s36, v90
	v_cmp_gt_u32_e32 vcc, 0x1000000, v2
	v_bfe_u32 v3, v2, 16, 8
	v_lshl_add_u32 v3, v3, 2, v5
	s_mov_b64 exec, vcc
	ds_add_u32 v3, v4
	s_mov_b64 exec, -1
	v_subrev_u32_e32 v2, s36, v91
	v_cmp_gt_u32_e32 vcc, 0x1000000, v2
	v_bfe_u32 v3, v2, 16, 8
	v_lshl_add_u32 v3, v3, 2, v5
	s_mov_b64 exec, vcc
	ds_add_u32 v3, v4
	s_mov_b64 exec, -1
	v_subrev_u32_e32 v2, s36, v92
	v_cmp_gt_u32_e32 vcc, 0x1000000, v2
	v_bfe_u32 v3, v2, 16, 8
	v_lshl_add_u32 v3, v3, 2, v5
	s_mov_b64 exec, vcc
	ds_add_u32 v3, v4
	s_mov_b64 exec, -1
	v_subrev_u32_e32 v2, s36, v93
	v_cmp_gt_u32_e32 vcc, 0x1000000, v2
	v_bfe_u32 v3, v2, 16, 8
	v_lshl_add_u32 v3, v3, 2, v5
	s_mov_b64 exec, vcc
	ds_add_u32 v3, v4
	s_mov_b64 exec, -1
	v_subrev_u32_e32 v2, s36, v94
	v_cmp_gt_u32_e32 vcc, 0x1000000, v2
	v_bfe_u32 v3, v2, 16, 8
	v_lshl_add_u32 v3, v3, 2, v5
	s_mov_b64 exec, vcc
	ds_add_u32 v3, v4
	s_mov_b64 exec, -1
	v_subrev_u32_e32 v2, s36, v95
	v_cmp_gt_u32_e32 vcc, 0x1000000, v2
	v_bfe_u32 v3, v2, 16, 8
	v_lshl_add_u32 v3, v3, 2, v5
	s_mov_b64 exec, vcc
	ds_add_u32 v3, v4
	s_mov_b64 exec, -1
	s_cmp_lt_i32 s38, 8
	s_cbranch_scc1 .Lsel_p2_done
	v_subrev_u32_e32 v2, s36, v96
	v_cmp_gt_u32_e32 vcc, 0x1000000, v2
	v_bfe_u32 v3, v2, 16, 8
	v_lshl_add_u32 v3, v3, 2, v5
	s_mov_b64 exec, vcc
	ds_add_u32 v3, v4
	s_mov_b64 exec, -1
	v_subrev_u32_e32 v2, s36, v97
	v_cmp_gt_u32_e32 vcc, 0x1000000, v2
	v_bfe_u32 v3, v2, 16, 8
	v_lshl_add_u32 v3, v3, 2, v5
	s_mov_b64 exec, vcc
	ds_add_u32 v3, v4
	s_mov_b64 exec, -1
	v_subrev_u32_e32 v2, s36, v98
	v_cmp_gt_u32_e32 vcc, 0x1000000, v2
	v_bfe_u32 v3, v2, 16, 8
	v_lshl_add_u32 v3, v3, 2, v5
	s_mov_b64 exec, vcc
	ds_add_u32 v3, v4
	s_mov_b64 exec, -1
	v_subrev_u32_e32 v2, s36, v99
	v_cmp_gt_u32_e32 vcc, 0x1000000, v2
	v_bfe_u32 v3, v2, 16, 8
	v_lshl_add_u32 v3, v3, 2, v5
	s_mov_b64 exec, vcc
	ds_add_u32 v3, v4
	s_mov_b64 exec, -1
	v_subrev_u32_e32 v2, s36, v100
	v_cmp_gt_u32_e32 vcc, 0x1000000, v2
	v_bfe_u32 v3, v2, 16, 8
	v_lshl_add_u32 v3, v3, 2, v5
	s_mov_b64 exec, vcc
	ds_add_u32 v3, v4
	s_mov_b64 exec, -1
	v_subrev_u32_e32 v2, s36, v101
	v_cmp_gt_u32_e32 vcc, 0x1000000, v2
	v_bfe_u32 v3, v2, 16, 8
	v_lshl_add_u32 v3, v3, 2, v5
	s_mov_b64 exec, vcc
	ds_add_u32 v3, v4
	s_mov_b64 exec, -1
	v_subrev_u32_e32 v2, s36, v102
	v_cmp_gt_u32_e32 vcc, 0x1000000, v2
	v_bfe_u32 v3, v2, 16, 8
	v_lshl_add_u32 v3, v3, 2, v5
	s_mov_b64 exec, vcc
	ds_add_u32 v3, v4
	s_mov_b64 exec, -1
	v_subrev_u32_e32 v2, s36, v103
	v_cmp_gt_u32_e32 vcc, 0x1000000, v2
	v_bfe_u32 v3, v2, 16, 8
	v_lshl_add_u32 v3, v3, 2, v5
	s_mov_b64 exec, vcc
	ds_add_u32 v3, v4
	s_mov_b64 exec, -1
	s_cmp_lt_i32 s38, 16
	s_cbranch_scc1 .Lsel_p2_done
	v_subrev_u32_e32 v2, s36, v104
	v_cmp_gt_u32_e32 vcc, 0x1000000, v2
	v_bfe_u32 v3, v2, 16, 8
	v_lshl_add_u32 v3, v3, 2, v5
	s_mov_b64 exec, vcc
	ds_add_u32 v3, v4
	s_mov_b64 exec, -1
	v_subrev_u32_e32 v2, s36, v105
	v_cmp_gt_u32_e32 vcc, 0x1000000, v2
	v_bfe_u32 v3, v2, 16, 8
	v_lshl_add_u32 v3, v3, 2, v5
	s_mov_b64 exec, vcc
	ds_add_u32 v3, v4
	s_mov_b64 exec, -1
	v_subrev_u32_e32 v2, s36, v106
	v_cmp_gt_u32_e32 vcc, 0x1000000, v2
	v_bfe_u32 v3, v2, 16, 8
	v_lshl_add_u32 v3, v3, 2, v5
	s_mov_b64 exec, vcc
	ds_add_u32 v3, v4
	s_mov_b64 exec, -1
	v_subrev_u32_e32 v2, s36, v107
	v_cmp_gt_u32_e32 vcc, 0x1000000, v2
	v_bfe_u32 v3, v2, 16, 8
	v_lshl_add_u32 v3, v3, 2, v5
	s_mov_b64 exec, vcc
	ds_add_u32 v3, v4
	s_mov_b64 exec, -1
	v_subrev_u32_e32 v2, s36, v108
	v_cmp_gt_u32_e32 vcc, 0x1000000, v2
	v_bfe_u32 v3, v2, 16, 8
	v_lshl_add_u32 v3, v3, 2, v5
	s_mov_b64 exec, vcc
	ds_add_u32 v3, v4
	s_mov_b64 exec, -1
	v_subrev_u32_e32 v2, s36, v109
	v_cmp_gt_u32_e32 vcc, 0x1000000, v2
	v_bfe_u32 v3, v2, 16, 8
	v_lshl_add_u32 v3, v3, 2, v5
	s_mov_b64 exec, vcc
	ds_add_u32 v3, v4
	s_mov_b64 exec, -1
	v_subrev_u32_e32 v2, s36, v110
	v_cmp_gt_u32_e32 vcc, 0x1000000, v2
	v_bfe_u32 v3, v2, 16, 8
	v_lshl_add_u32 v3, v3, 2, v5
	s_mov_b64 exec, vcc
	ds_add_u32 v3, v4
	s_mov_b64 exec, -1
	v_subrev_u32_e32 v2, s36, v111
	v_cmp_gt_u32_e32 vcc, 0x1000000, v2
	v_bfe_u32 v3, v2, 16, 8
	v_lshl_add_u32 v3, v3, 2, v5
	s_mov_b64 exec, vcc
	ds_add_u32 v3, v4
	s_mov_b64 exec, -1
	s_cmp_lt_i32 s38, 24
	s_cbranch_scc1 .Lsel_p2_done
	v_subrev_u32_e32 v2, s36, v112
	v_cmp_gt_u32_e32 vcc, 0x1000000, v2
	v_bfe_u32 v3, v2, 16, 8
	v_lshl_add_u32 v3, v3, 2, v5
	s_mov_b64 exec, vcc
	ds_add_u32 v3, v4
	s_mov_b64 exec, -1
	v_subrev_u32_e32 v2, s36, v113
	v_cmp_gt_u32_e32 vcc, 0x1000000, v2
	v_bfe_u32 v3, v2, 16, 8
	v_lshl_add_u32 v3, v3, 2, v5
	s_mov_b64 exec, vcc
	ds_add_u32 v3, v4
	s_mov_b64 exec, -1
	v_subrev_u32_e32 v2, s36, v114
	v_cmp_gt_u32_e32 vcc, 0x1000000, v2
	v_bfe_u32 v3, v2, 16, 8
	v_lshl_add_u32 v3, v3, 2, v5
	s_mov_b64 exec, vcc
	ds_add_u32 v3, v4
	s_mov_b64 exec, -1
	v_subrev_u32_e32 v2, s36, v115
	v_cmp_gt_u32_e32 vcc, 0x1000000, v2
	v_bfe_u32 v3, v2, 16, 8
	v_lshl_add_u32 v3, v3, 2, v5
	s_mov_b64 exec, vcc
	ds_add_u32 v3, v4
	s_mov_b64 exec, -1
	v_subrev_u32_e32 v2, s36, v116
	v_cmp_gt_u32_e32 vcc, 0x1000000, v2
	v_bfe_u32 v3, v2, 16, 8
	v_lshl_add_u32 v3, v3, 2, v5
	s_mov_b64 exec, vcc
	ds_add_u32 v3, v4
	s_mov_b64 exec, -1
	v_subrev_u32_e32 v2, s36, v117
	v_cmp_gt_u32_e32 vcc, 0x1000000, v2
	v_bfe_u32 v3, v2, 16, 8
	v_lshl_add_u32 v3, v3, 2, v5
	s_mov_b64 exec, vcc
	ds_add_u32 v3, v4
	s_mov_b64 exec, -1
	v_subrev_u32_e32 v2, s36, v118
	v_cmp_gt_u32_e32 vcc, 0x1000000, v2
	v_bfe_u32 v3, v2, 16, 8
	v_lshl_add_u32 v3, v3, 2, v5
	s_mov_b64 exec, vcc
	ds_add_u32 v3, v4
	s_mov_b64 exec, -1
	v_subrev_u32_e32 v2, s36, v119
	v_cmp_gt_u32_e32 vcc, 0x1000000, v2
	v_bfe_u32 v3, v2, 16, 8
	v_lshl_add_u32 v3, v3, 2, v5
	s_mov_b64 exec, vcc
	ds_add_u32 v3, v4
	s_mov_b64 exec, -1
	s_cmp_lt_i32 s38, 32
	s_cbranch_scc1 .Lsel_p2_done
	v_subrev_u32_e32 v2, s36, v120
	v_cmp_gt_u32_e32 vcc, 0x1000000, v2
	v_bfe_u32 v3, v2, 16, 8
	v_lshl_add_u32 v3, v3, 2, v5
	s_mov_b64 exec, vcc
	ds_add_u32 v3, v4
	s_mov_b64 exec, -1
	v_subrev_u32_e32 v2, s36, v121
	v_cmp_gt_u32_e32 vcc, 0x1000000, v2
	v_bfe_u32 v3, v2, 16, 8
	v_lshl_add_u32 v3, v3, 2, v5
	s_mov_b64 exec, vcc
	ds_add_u32 v3, v4
	s_mov_b64 exec, -1
	v_subrev_u32_e32 v2, s36, v122
	v_cmp_gt_u32_e32 vcc, 0x1000000, v2
	v_bfe_u32 v3, v2, 16, 8
	v_lshl_add_u32 v3, v3, 2, v5
	s_mov_b64 exec, vcc
	ds_add_u32 v3, v4
	s_mov_b64 exec, -1
	v_subrev_u32_e32 v2, s36, v123
	v_cmp_gt_u32_e32 vcc, 0x1000000, v2
	v_bfe_u32 v3, v2, 16, 8
	v_lshl_add_u32 v3, v3, 2, v5
	s_mov_b64 exec, vcc
	ds_add_u32 v3, v4
	s_mov_b64 exec, -1
	v_subrev_u32_e32 v2, s36, v124
	v_cmp_gt_u32_e32 vcc, 0x1000000, v2
	v_bfe_u32 v3, v2, 16, 8
	v_lshl_add_u32 v3, v3, 2, v5
	s_mov_b64 exec, vcc
	ds_add_u32 v3, v4
	s_mov_b64 exec, -1
	v_subrev_u32_e32 v2, s36, v125
	v_cmp_gt_u32_e32 vcc, 0x1000000, v2
	v_bfe_u32 v3, v2, 16, 8
	v_lshl_add_u32 v3, v3, 2, v5
	s_mov_b64 exec, vcc
	ds_add_u32 v3, v4
	s_mov_b64 exec, -1
	v_subrev_u32_e32 v2, s36, v126
	v_cmp_gt_u32_e32 vcc, 0x1000000, v2
	v_bfe_u32 v3, v2, 16, 8
	v_lshl_add_u32 v3, v3, 2, v5
	s_mov_b64 exec, vcc
	ds_add_u32 v3, v4
	s_mov_b64 exec, -1
	v_subrev_u32_e32 v2, s36, v127
	v_cmp_gt_u32_e32 vcc, 0x1000000, v2
	v_bfe_u32 v3, v2, 16, 8
	v_lshl_add_u32 v3, v3, 2, v5
	s_mov_b64 exec, vcc
	ds_add_u32 v3, v4
	s_mov_b64 exec, -1
	s_cmp_lt_i32 s38, 40
	s_cbranch_scc1 .Lsel_p2_done
	v_subrev_u32_e32 v2, s36, v128
	v_cmp_gt_u32_e32 vcc, 0x1000000, v2
	v_bfe_u32 v3, v2, 16, 8
	v_lshl_add_u32 v3, v3, 2, v5
	s_mov_b64 exec, vcc
	ds_add_u32 v3, v4
	s_mov_b64 exec, -1
	v_subrev_u32_e32 v2, s36, v129
	v_cmp_gt_u32_e32 vcc, 0x1000000, v2
	v_bfe_u32 v3, v2, 16, 8
	v_lshl_add_u32 v3, v3, 2, v5
	s_mov_b64 exec, vcc
	ds_add_u32 v3, v4
	s_mov_b64 exec, -1
	v_subrev_u32_e32 v2, s36, v130
	v_cmp_gt_u32_e32 vcc, 0x1000000, v2
	v_bfe_u32 v3, v2, 16, 8
	v_lshl_add_u32 v3, v3, 2, v5
	s_mov_b64 exec, vcc
	ds_add_u32 v3, v4
	s_mov_b64 exec, -1
	v_subrev_u32_e32 v2, s36, v131
	v_cmp_gt_u32_e32 vcc, 0x1000000, v2
	v_bfe_u32 v3, v2, 16, 8
	v_lshl_add_u32 v3, v3, 2, v5
	s_mov_b64 exec, vcc
	ds_add_u32 v3, v4
	s_mov_b64 exec, -1
	v_subrev_u32_e32 v2, s36, v132
	v_cmp_gt_u32_e32 vcc, 0x1000000, v2
	v_bfe_u32 v3, v2, 16, 8
	v_lshl_add_u32 v3, v3, 2, v5
	s_mov_b64 exec, vcc
	ds_add_u32 v3, v4
	s_mov_b64 exec, -1
	v_subrev_u32_e32 v2, s36, v133
	v_cmp_gt_u32_e32 vcc, 0x1000000, v2
	v_bfe_u32 v3, v2, 16, 8
	v_lshl_add_u32 v3, v3, 2, v5
	s_mov_b64 exec, vcc
	ds_add_u32 v3, v4
	s_mov_b64 exec, -1
	v_subrev_u32_e32 v2, s36, v134
	v_cmp_gt_u32_e32 vcc, 0x1000000, v2
	v_bfe_u32 v3, v2, 16, 8
	v_lshl_add_u32 v3, v3, 2, v5
	s_mov_b64 exec, vcc
	ds_add_u32 v3, v4
	s_mov_b64 exec, -1
	v_subrev_u32_e32 v2, s36, v135
	v_cmp_gt_u32_e32 vcc, 0x1000000, v2
	v_bfe_u32 v3, v2, 16, 8
	v_lshl_add_u32 v3, v3, 2, v5
	s_mov_b64 exec, vcc
	ds_add_u32 v3, v4
	s_mov_b64 exec, -1
	s_cmp_lt_i32 s38, 48
	s_cbranch_scc1 .Lsel_p2_done
	v_subrev_u32_e32 v2, s36, v136
	v_cmp_gt_u32_e32 vcc, 0x1000000, v2
	v_bfe_u32 v3, v2, 16, 8
	v_lshl_add_u32 v3, v3, 2, v5
	s_mov_b64 exec, vcc
	ds_add_u32 v3, v4
	s_mov_b64 exec, -1
	v_subrev_u32_e32 v2, s36, v137
	v_cmp_gt_u32_e32 vcc, 0x1000000, v2
	v_bfe_u32 v3, v2, 16, 8
	v_lshl_add_u32 v3, v3, 2, v5
	s_mov_b64 exec, vcc
	ds_add_u32 v3, v4
	s_mov_b64 exec, -1
	v_subrev_u32_e32 v2, s36, v138
	v_cmp_gt_u32_e32 vcc, 0x1000000, v2
	v_bfe_u32 v3, v2, 16, 8
	v_lshl_add_u32 v3, v3, 2, v5
	s_mov_b64 exec, vcc
	ds_add_u32 v3, v4
	s_mov_b64 exec, -1
	v_subrev_u32_e32 v2, s36, v139
	v_cmp_gt_u32_e32 vcc, 0x1000000, v2
	v_bfe_u32 v3, v2, 16, 8
	v_lshl_add_u32 v3, v3, 2, v5
	s_mov_b64 exec, vcc
	ds_add_u32 v3, v4
	s_mov_b64 exec, -1
	v_subrev_u32_e32 v2, s36, v140
	v_cmp_gt_u32_e32 vcc, 0x1000000, v2
	v_bfe_u32 v3, v2, 16, 8
	v_lshl_add_u32 v3, v3, 2, v5
	s_mov_b64 exec, vcc
	ds_add_u32 v3, v4
	s_mov_b64 exec, -1
	v_subrev_u32_e32 v2, s36, v141
	v_cmp_gt_u32_e32 vcc, 0x1000000, v2
	v_bfe_u32 v3, v2, 16, 8
	v_lshl_add_u32 v3, v3, 2, v5
	s_mov_b64 exec, vcc
	ds_add_u32 v3, v4
	s_mov_b64 exec, -1
	v_subrev_u32_e32 v2, s36, v142
	v_cmp_gt_u32_e32 vcc, 0x1000000, v2
	v_bfe_u32 v3, v2, 16, 8
	v_lshl_add_u32 v3, v3, 2, v5
	s_mov_b64 exec, vcc
	ds_add_u32 v3, v4
	s_mov_b64 exec, -1
	v_subrev_u32_e32 v2, s36, v143
	v_cmp_gt_u32_e32 vcc, 0x1000000, v2
	v_bfe_u32 v3, v2, 16, 8
	v_lshl_add_u32 v3, v3, 2, v5
	s_mov_b64 exec, vcc
	ds_add_u32 v3, v4
	s_mov_b64 exec, -1
	s_cmp_lt_i32 s38, 56
	s_cbranch_scc1 .Lsel_p2_done
	v_subrev_u32_e32 v2, s36, v144
	v_cmp_gt_u32_e32 vcc, 0x1000000, v2
	v_bfe_u32 v3, v2, 16, 8
	v_lshl_add_u32 v3, v3, 2, v5
	s_mov_b64 exec, vcc
	ds_add_u32 v3, v4
	s_mov_b64 exec, -1
	v_subrev_u32_e32 v2, s36, v145
	v_cmp_gt_u32_e32 vcc, 0x1000000, v2
	v_bfe_u32 v3, v2, 16, 8
	v_lshl_add_u32 v3, v3, 2, v5
	s_mov_b64 exec, vcc
	ds_add_u32 v3, v4
	s_mov_b64 exec, -1
	v_subrev_u32_e32 v2, s36, v146
	v_cmp_gt_u32_e32 vcc, 0x1000000, v2
	v_bfe_u32 v3, v2, 16, 8
	v_lshl_add_u32 v3, v3, 2, v5
	s_mov_b64 exec, vcc
	ds_add_u32 v3, v4
	s_mov_b64 exec, -1
	v_subrev_u32_e32 v2, s36, v147
	v_cmp_gt_u32_e32 vcc, 0x1000000, v2
	v_bfe_u32 v3, v2, 16, 8
	v_lshl_add_u32 v3, v3, 2, v5
	s_mov_b64 exec, vcc
	ds_add_u32 v3, v4
	s_mov_b64 exec, -1
	v_subrev_u32_e32 v2, s36, v148
	v_cmp_gt_u32_e32 vcc, 0x1000000, v2
	v_bfe_u32 v3, v2, 16, 8
	v_lshl_add_u32 v3, v3, 2, v5
	s_mov_b64 exec, vcc
	ds_add_u32 v3, v4
	s_mov_b64 exec, -1
	v_subrev_u32_e32 v2, s36, v149
	v_cmp_gt_u32_e32 vcc, 0x1000000, v2
	v_bfe_u32 v3, v2, 16, 8
	v_lshl_add_u32 v3, v3, 2, v5
	s_mov_b64 exec, vcc
	ds_add_u32 v3, v4
	s_mov_b64 exec, -1
	v_subrev_u32_e32 v2, s36, v150
	v_cmp_gt_u32_e32 vcc, 0x1000000, v2
	v_bfe_u32 v3, v2, 16, 8
	v_lshl_add_u32 v3, v3, 2, v5
	s_mov_b64 exec, vcc
	ds_add_u32 v3, v4
	s_mov_b64 exec, -1
	v_subrev_u32_e32 v2, s36, v151
	v_cmp_gt_u32_e32 vcc, 0x1000000, v2
	v_bfe_u32 v3, v2, 16, 8
	v_lshl_add_u32 v3, v3, 2, v5
	s_mov_b64 exec, vcc
	ds_add_u32 v3, v4
	s_mov_b64 exec, -1
.Lsel_p2_done:
	s_waitcnt lgkmcnt(0)
	ds_read_b128 v[8:11], v7
	s_waitcnt lgkmcnt(0)
	ds_write_b128 v6, v[24:27]
	v_add3_u32 v12, v8, v9, v10
	v_add_u32_e32 v12, v12, v11
	v_mov_b32_e32 v13, v12
	s_nop 1
	v_add_u32_dpp v13, v13, v13 row_shr:1 row_mask:0xf bank_mask:0xf
	s_nop 1
	v_add_u32_dpp v13, v13, v13 row_shr:2 row_mask:0xf bank_mask:0xf
	s_nop 1
	v_add_u32_dpp v13, v13, v13 row_shr:4 row_mask:0xf bank_mask:0xf
	s_nop 1
	v_add_u32_dpp v13, v13, v13 row_shr:8 row_mask:0xf bank_mask:0xf
	s_nop 1
	v_readlane_b32 s40, v13, 15
	v_readlane_b32 s41, v13, 31
	v_readlane_b32 s42, v13, 47
	s_add_i32 s41, s40, s41
	s_add_i32 s42, s41, s42
	s_mov_b32 exec_lo, 0xffff0000
	s_mov_b32 exec_hi, 0
	v_add_u32_e32 v13, s40, v13
	s_mov_b32 exec_lo, 0
	s_mov_b32 exec_hi, 0xffff
	v_add_u32_e32 v13, s41, v13
	s_mov_b32 exec_hi, 0xffff0000
	v_add_u32_e32 v13, s42, v13
	s_mov_b64 exec, -1
	v_sub_u32_e32 v14, v13, v12
	v_add_u32_e32 v15, v14, v11
	v_add_u32_e32 v16, v15, v10
	v_add_u32_e32 v17, v16, v9
	v_cmp_gt_u32_e32 vcc, s29, v14
	s_bcnt1_i32_b64 s30, vcc
	v_cmp_gt_u32_e32 vcc, s29, v15
	s_bcnt1_i32_b64 s4, vcc
	s_add_i32 s30, s30, s4
	v_cmp_gt_u32_e32 vcc, s29, v16
	s_bcnt1_i32_b64 s4, vcc
	s_add_i32 s30, s30, s4
	v_cmp_gt_u32_e32 vcc, s29, v17
	s_bcnt1_i32_b64 s4, vcc
	s_add_i32 s30, s30, s4
	s_add_i32 s30, s30, -1
	s_lshr_b32 s5, s30, 2
	s_and_b32 s6, s30, 3
	s_sub_i32 s37, 0xff, s30
	s_nop 3
	v_readlane_b32 s40, v14, s5
	v_readlane_b32 s41, v15, s5
	v_readlane_b32 s42, v16, s5
	v_readlane_b32 s43, v17, s5
	s_cmp_eq_u32 s6, 1
	s_cselect_b32 s40, s41, s40
	s_cmp_eq_u32 s6, 2
	s_cselect_b32 s40, s42, s40
	s_cmp_eq_u32 s6, 3
	s_cselect_b32 s40, s43, s40
	s_lshl_b32 s36, s34, 8
	s_or_b32 s36, s36, s37
	s_lshl_b32 s37, s36, 16
	s_or_b32 s44, s37, 0xffff
	s_add_i32 s45, s35, s40
	v_mov_b32_e32 v18, 0
	v_mov_b32_e32 v19, s45
	v_cmp_lt_u32_e32 vcc, s44, v88
	v_cmp_le_u32_e64 s[0:1], s37, v88
	s_bcnt1_i32_b64 s4, vcc
	v_mbcnt_lo_u32_b32 v20, vcc_lo, v18
	v_mbcnt_hi_u32_b32 v20, vcc_hi, v20
	v_add_u32_e32 v18, s4, v18
	v_lshlrev_b32_e32 v21, 2, v20
	v_mov_b32_e32 v23, v34
	s_mov_b64 exec, vcc
	global_store_dword v21, v23, s[2:3]
	s_mov_b64 exec, -1
	s_andn2_b64 s[0:1], s[0:1], vcc
	s_cbranch_scc1 .Lsel_eq0
.Lsel_eqb0:
	v_cmp_lt_u32_e32 vcc, s44, v89
	v_cmp_le_u32_e64 s[0:1], s37, v89
	s_bcnt1_i32_b64 s4, vcc
	v_mbcnt_lo_u32_b32 v20, vcc_lo, v18
	v_mbcnt_hi_u32_b32 v20, vcc_hi, v20
	v_add_u32_e32 v18, s4, v18
	v_lshlrev_b32_e32 v21, 2, v20
	v_or_b32_e32 v23, 64, v34
	s_mov_b64 exec, vcc
	global_store_dword v21, v23, s[2:3]
	s_mov_b64 exec, -1
	s_andn2_b64 s[0:1], s[0:1], vcc
	s_cbranch_scc1 .Lsel_eq1
.Lsel_eqb1:
	v_cmp_lt_u32_e32 vcc, s44, v90
	v_cmp_le_u32_e64 s[0:1], s37, v90
	s_bcnt1_i32_b64 s4, vcc
	v_mbcnt_lo_u32_b32 v20, vcc_lo, v18
	v_mbcnt_hi_u32_b32 v20, vcc_hi, v20
	v_add_u32_e32 v18, s4, v18
	v_lshlrev_b32_e32 v21, 2, v20
	v_or_b32_e32 v23, 128, v34
	s_mov_b64 exec, vcc
	global_store_dword v21, v23, s[2:3]
	s_mov_b64 exec, -1
	s_andn2_b64 s[0:1], s[0:1], vcc
	s_cbranch_scc1 .Lsel_eq2
.Lsel_eqb2:
	v_cmp_lt_u32_e32 vcc, s44, v91
	v_cmp_le_u32_e64 s[0:1], s37, v91
	s_bcnt1_i32_b64 s4, vcc
	v_mbcnt_lo_u32_b32 v20, vcc_lo, v18
	v_mbcnt_hi_u32_b32 v20, vcc_hi, v20
	v_add_u32_e32 v18, s4, v18
	v_lshlrev_b32_e32 v21, 2, v20
	v_or_b32_e32 v23, 192, v34
	s_mov_b64 exec, vcc
	global_store_dword v21, v23, s[2:3]
	s_mov_b64 exec, -1
	s_andn2_b64 s[0:1], s[0:1], vcc
	s_cbranch_scc1 .Lsel_eq3
.Lsel_eqb3:
	v_cmp_lt_u32_e32 vcc, s44, v92
	v_cmp_le_u32_e64 s[0:1], s37, v92
	s_bcnt1_i32_b64 s4, vcc
	v_mbcnt_lo_u32_b32 v20, vcc_lo, v18
	v_mbcnt_hi_u32_b32 v20, vcc_hi, v20
	v_add_u32_e32 v18, s4, v18
	v_lshlrev_b32_e32 v21, 2, v20
	v_or_b32_e32 v23, 256, v34
	s_mov_b64 exec, vcc
	global_store_dword v21, v23, s[2:3]
	s_mov_b64 exec, -1
	s_andn2_b64 s[0:1], s[0:1], vcc
	s_cbranch_scc1 .Lsel_eq4
.Lsel_eqb4:
	v_cmp_lt_u32_e32 vcc, s44, v93
	v_cmp_le_u32_e64 s[0:1], s37, v93
	s_bcnt1_i32_b64 s4, vcc
	v_mbcnt_lo_u32_b32 v20, vcc_lo, v18
	v_mbcnt_hi_u32_b32 v20, vcc_hi, v20
	v_add_u32_e32 v18, s4, v18
	v_lshlrev_b32_e32 v21, 2, v20
	v_or_b32_e32 v23, 320, v34
	s_mov_b64 exec, vcc
	global_store_dword v21, v23, s[2:3]
	s_mov_b64 exec, -1
	s_andn2_b64 s[0:1], s[0:1], vcc
	s_cbranch_scc1 .Lsel_eq5
.Lsel_eqb5:
	v_cmp_lt_u32_e32 vcc, s44, v94
	v_cmp_le_u32_e64 s[0:1], s37, v94
	s_bcnt1_i32_b64 s4, vcc
	v_mbcnt_lo_u32_b32 v20, vcc_lo, v18
	v_mbcnt_hi_u32_b32 v20, vcc_hi, v20
	v_add_u32_e32 v18, s4, v18
	v_lshlrev_b32_e32 v21, 2, v20
	v_or_b32_e32 v23, 384, v34
	s_mov_b64 exec, vcc
	global_store_dword v21, v23, s[2:3]
	s_mov_b64 exec, -1
	s_andn2_b64 s[0:1], s[0:1], vcc
	s_cbranch_scc1 .Lsel_eq6
.Lsel_eqb6:
	v_cmp_lt_u32_e32 vcc, s44, v95
	v_cmp_le_u32_e64 s[0:1], s37, v95
	s_bcnt1_i32_b64 s4, vcc
	v_mbcnt_lo_u32_b32 v20, vcc_lo, v18
	v_mbcnt_hi_u32_b32 v20, vcc_hi, v20
	v_add_u32_e32 v18, s4, v18
	v_lshlrev_b32_e32 v21, 2, v20
	v_or_b32_e32 v23, 448, v34
	s_mov_b64 exec, vcc
	global_store_dword v21, v23, s[2:3]
	s_mov_b64 exec, -1
	s_andn2_b64 s[0:1], s[0:1], vcc
	s_cbranch_scc1 .Lsel_eq7
.Lsel_eqb7:
	s_cmp_lt_i32 s38, 8
	s_cbranch_scc1 .Lsel_cp_done
	v_cmp_lt_u32_e32 vcc, s44, v96
	v_cmp_le_u32_e64 s[0:1], s37, v96
	s_bcnt1_i32_b64 s4, vcc
	v_mbcnt_lo_u32_b32 v20, vcc_lo, v18
	v_mbcnt_hi_u32_b32 v20, vcc_hi, v20
	v_add_u32_e32 v18, s4, v18
	v_lshlrev_b32_e32 v21, 2, v20
	v_or_b32_e32 v23, 512, v34
	s_mov_b64 exec, vcc
	global_store_dword v21, v23, s[2:3]
	s_mov_b64 exec, -1
	s_andn2_b64 s[0:1], s[0:1], vcc
	s_cbranch_scc1 .Lsel_eq8
.Lsel_eqb8:
	v_cmp_lt_u32_e32 vcc, s44, v97
	v_cmp_le_u32_e64 s[0:1], s37, v97
	s_bcnt1_i32_b64 s4, vcc
	v_mbcnt_lo_u32_b32 v20, vcc_lo, v18
	v_mbcnt_hi_u32_b32 v20, vcc_hi, v20
	v_add_u32_e32 v18, s4, v18
	v_lshlrev_b32_e32 v21, 2, v20
	v_or_b32_e32 v23, 576, v34
	s_mov_b64 exec, vcc
	global_store_dword v21, v23, s[2:3]
	s_mov_b64 exec, -1
	s_andn2_b64 s[0:1], s[0:1], vcc
	s_cbranch_scc1 .Lsel_eq9
.Lsel_eqb9:
	v_cmp_lt_u32_e32 vcc, s44, v98
	v_cmp_le_u32_e64 s[0:1], s37, v98
	s_bcnt1_i32_b64 s4, vcc
	v_mbcnt_lo_u32_b32 v20, vcc_lo, v18
	v_mbcnt_hi_u32_b32 v20, vcc_hi, v20
	v_add_u32_e32 v18, s4, v18
	v_lshlrev_b32_e32 v21, 2, v20
	v_or_b32_e32 v23, 640, v34
	s_mov_b64 exec, vcc
	global_store_dword v21, v23, s[2:3]
	s_mov_b64 exec, -1
	s_andn2_b64 s[0:1], s[0:1], vcc
	s_cbranch_scc1 .Lsel_eq10
.Lsel_eqb10:
	v_cmp_lt_u32_e32 vcc, s44, v99
	v_cmp_le_u32_e64 s[0:1], s37, v99
	s_bcnt1_i32_b64 s4, vcc
	v_mbcnt_lo_u32_b32 v20, vcc_lo, v18
	v_mbcnt_hi_u32_b32 v20, vcc_hi, v20
	v_add_u32_e32 v18, s4, v18
	v_lshlrev_b32_e32 v21, 2, v20
	v_or_b32_e32 v23, 704, v34
	s_mov_b64 exec, vcc
	global_store_dword v21, v23, s[2:3]
	s_mov_b64 exec, -1
	s_andn2_b64 s[0:1], s[0:1], vcc
	s_cbranch_scc1 .Lsel_eq11
.Lsel_eqb11:
	v_cmp_lt_u32_e32 vcc, s44, v100
	v_cmp_le_u32_e64 s[0:1], s37, v100
	s_bcnt1_i32_b64 s4, vcc
	v_mbcnt_lo_u32_b32 v20, vcc_lo, v18
	v_mbcnt_hi_u32_b32 v20, vcc_hi, v20
	v_add_u32_e32 v18, s4, v18
	v_lshlrev_b32_e32 v21, 2, v20
	v_or_b32_e32 v23, 768, v34
	s_mov_b64 exec, vcc
	global_store_dword v21, v23, s[2:3]
	s_mov_b64 exec, -1
	s_andn2_b64 s[0:1], s[0:1], vcc
	s_cbranch_scc1 .Lsel_eq12
.Lsel_eqb12:
	v_cmp_lt_u32_e32 vcc, s44, v101
	v_cmp_le_u32_e64 s[0:1], s37, v101
	s_bcnt1_i32_b64 s4, vcc
	v_mbcnt_lo_u32_b32 v20, vcc_lo, v18
	v_mbcnt_hi_u32_b32 v20, vcc_hi, v20
	v_add_u32_e32 v18, s4, v18
	v_lshlrev_b32_e32 v21, 2, v20
	v_or_b32_e32 v23, 832, v34
	s_mov_b64 exec, vcc
	global_store_dword v21, v23, s[2:3]
	s_mov_b64 exec, -1
	s_andn2_b64 s[0:1], s[0:1], vcc
	s_cbranch_scc1 .Lsel_eq13
.Lsel_eqb13:
	v_cmp_lt_u32_e32 vcc, s44, v102
	v_cmp_le_u32_e64 s[0:1], s37, v102
	s_bcnt1_i32_b64 s4, vcc
	v_mbcnt_lo_u32_b32 v20, vcc_lo, v18
	v_mbcnt_hi_u32_b32 v20, vcc_hi, v20
	v_add_u32_e32 v18, s4, v18
	v_lshlrev_b32_e32 v21, 2, v20
	v_or_b32_e32 v23, 896, v34
	s_mov_b64 exec, vcc
	global_store_dword v21, v23, s[2:3]
	s_mov_b64 exec, -1
	s_andn2_b64 s[0:1], s[0:1], vcc
	s_cbranch_scc1 .Lsel_eq14
.Lsel_eqb14:
	v_cmp_lt_u32_e32 vcc, s44, v103
	v_cmp_le_u32_e64 s[0:1], s37, v103
	s_bcnt1_i32_b64 s4, vcc
	v_mbcnt_lo_u32_b32 v20, vcc_lo, v18
	v_mbcnt_hi_u32_b32 v20, vcc_hi, v20
	v_add_u32_e32 v18, s4, v18
	v_lshlrev_b32_e32 v21, 2, v20
	v_or_b32_e32 v23, 960, v34
	s_mov_b64 exec, vcc
	global_store_dword v21, v23, s[2:3]
	s_mov_b64 exec, -1
	s_andn2_b64 s[0:1], s[0:1], vcc
	s_cbranch_scc1 .Lsel_eq15
.Lsel_eqb15:
	s_cmp_lt_i32 s38, 16
	s_cbranch_scc1 .Lsel_cp_done
	v_cmp_lt_u32_e32 vcc, s44, v104
	v_cmp_le_u32_e64 s[0:1], s37, v104
	s_bcnt1_i32_b64 s4, vcc
	v_mbcnt_lo_u32_b32 v20, vcc_lo, v18
	v_mbcnt_hi_u32_b32 v20, vcc_hi, v20
	v_add_u32_e32 v18, s4, v18
	v_lshlrev_b32_e32 v21, 2, v20
	v_or_b32_e32 v23, 1024, v34
	s_mov_b64 exec, vcc
	global_store_dword v21, v23, s[2:3]
	s_mov_b64 exec, -1
	s_andn2_b64 s[0:1], s[0:1], vcc
	s_cbranch_scc1 .Lsel_eq16
.Lsel_eqb16:
	v_cmp_lt_u32_e32 vcc, s44, v105
	v_cmp_le_u32_e64 s[0:1], s37, v105
	s_bcnt1_i32_b64 s4, vcc
	v_mbcnt_lo_u32_b32 v20, vcc_lo, v18
	v_mbcnt_hi_u32_b32 v20, vcc_hi, v20
	v_add_u32_e32 v18, s4, v18
	v_lshlrev_b32_e32 v21, 2, v20
	v_or_b32_e32 v23, 1088, v34
	s_mov_b64 exec, vcc
	global_store_dword v21, v23, s[2:3]
	s_mov_b64 exec, -1
	s_andn2_b64 s[0:1], s[0:1], vcc
	s_cbranch_scc1 .Lsel_eq17
.Lsel_eqb17:
	v_cmp_lt_u32_e32 vcc, s44, v106
	v_cmp_le_u32_e64 s[0:1], s37, v106
	s_bcnt1_i32_b64 s4, vcc
	v_mbcnt_lo_u32_b32 v20, vcc_lo, v18
	v_mbcnt_hi_u32_b32 v20, vcc_hi, v20
	v_add_u32_e32 v18, s4, v18
	v_lshlrev_b32_e32 v21, 2, v20
	v_or_b32_e32 v23, 1152, v34
	s_mov_b64 exec, vcc
	global_store_dword v21, v23, s[2:3]
	s_mov_b64 exec, -1
	s_andn2_b64 s[0:1], s[0:1], vcc
	s_cbranch_scc1 .Lsel_eq18
.Lsel_eqb18:
	v_cmp_lt_u32_e32 vcc, s44, v107
	v_cmp_le_u32_e64 s[0:1], s37, v107
	s_bcnt1_i32_b64 s4, vcc
	v_mbcnt_lo_u32_b32 v20, vcc_lo, v18
	v_mbcnt_hi_u32_b32 v20, vcc_hi, v20
	v_add_u32_e32 v18, s4, v18
	v_lshlrev_b32_e32 v21, 2, v20
	v_or_b32_e32 v23, 1216, v34
	s_mov_b64 exec, vcc
	global_store_dword v21, v23, s[2:3]
	s_mov_b64 exec, -1
	s_andn2_b64 s[0:1], s[0:1], vcc
	s_cbranch_scc1 .Lsel_eq19
.Lsel_eqb19:
	v_cmp_lt_u32_e32 vcc, s44, v108
	v_cmp_le_u32_e64 s[0:1], s37, v108
	s_bcnt1_i32_b64 s4, vcc
	v_mbcnt_lo_u32_b32 v20, vcc_lo, v18
	v_mbcnt_hi_u32_b32 v20, vcc_hi, v20
	v_add_u32_e32 v18, s4, v18
	v_lshlrev_b32_e32 v21, 2, v20
	v_or_b32_e32 v23, 1280, v34
	s_mov_b64 exec, vcc
	global_store_dword v21, v23, s[2:3]
	s_mov_b64 exec, -1
	s_andn2_b64 s[0:1], s[0:1], vcc
	s_cbranch_scc1 .Lsel_eq20
.Lsel_eqb20:
	v_cmp_lt_u32_e32 vcc, s44, v109
	v_cmp_le_u32_e64 s[0:1], s37, v109
	s_bcnt1_i32_b64 s4, vcc
	v_mbcnt_lo_u32_b32 v20, vcc_lo, v18
	v_mbcnt_hi_u32_b32 v20, vcc_hi, v20
	v_add_u32_e32 v18, s4, v18
	v_lshlrev_b32_e32 v21, 2, v20
	v_or_b32_e32 v23, 1344, v34
	s_mov_b64 exec, vcc
	global_store_dword v21, v23, s[2:3]
	s_mov_b64 exec, -1
	s_andn2_b64 s[0:1], s[0:1], vcc
	s_cbranch_scc1 .Lsel_eq21
.Lsel_eqb21:
	v_cmp_lt_u32_e32 vcc, s44, v110
	v_cmp_le_u32_e64 s[0:1], s37, v110
	s_bcnt1_i32_b64 s4, vcc
	v_mbcnt_lo_u32_b32 v20, vcc_lo, v18
	v_mbcnt_hi_u32_b32 v20, vcc_hi, v20
	v_add_u32_e32 v18, s4, v18
	v_lshlrev_b32_e32 v21, 2, v20
	v_or_b32_e32 v23, 1408, v34
	s_mov_b64 exec, vcc
	global_store_dword v21, v23, s[2:3]
	s_mov_b64 exec, -1
	s_andn2_b64 s[0:1], s[0:1], vcc
	s_cbranch_scc1 .Lsel_eq22
.Lsel_eqb22:
	v_cmp_lt_u32_e32 vcc, s44, v111
	v_cmp_le_u32_e64 s[0:1], s37, v111
	s_bcnt1_i32_b64 s4, vcc
	v_mbcnt_lo_u32_b32 v20, vcc_lo, v18
	v_mbcnt_hi_u32_b32 v20, vcc_hi, v20
	v_add_u32_e32 v18, s4, v18
	v_lshlrev_b32_e32 v21, 2, v20
	v_or_b32_e32 v23, 1472, v34
	s_mov_b64 exec, vcc
	global_store_dword v21, v23, s[2:3]
	s_mov_b64 exec, -1
	s_andn2_b64 s[0:1], s[0:1], vcc
	s_cbranch_scc1 .Lsel_eq23
.Lsel_eqb23:
	s_cmp_lt_i32 s38, 24
	s_cbranch_scc1 .Lsel_cp_done
	v_cmp_lt_u32_e32 vcc, s44, v112
	v_cmp_le_u32_e64 s[0:1], s37, v112
	s_bcnt1_i32_b64 s4, vcc
	v_mbcnt_lo_u32_b32 v20, vcc_lo, v18
	v_mbcnt_hi_u32_b32 v20, vcc_hi, v20
	v_add_u32_e32 v18, s4, v18
	v_lshlrev_b32_e32 v21, 2, v20
	v_or_b32_e32 v23, 1536, v34
	s_mov_b64 exec, vcc
	global_store_dword v21, v23, s[2:3]
	s_mov_b64 exec, -1
	s_andn2_b64 s[0:1], s[0:1], vcc
	s_cbranch_scc1 .Lsel_eq24
.Lsel_eqb24:
	v_cmp_lt_u32_e32 vcc, s44, v113
	v_cmp_le_u32_e64 s[0:1], s37, v113
	s_bcnt1_i32_b64 s4, vcc
	v_mbcnt_lo_u32_b32 v20, vcc_lo, v18
	v_mbcnt_hi_u32_b32 v20, vcc_hi, v20
	v_add_u32_e32 v18, s4, v18
	v_lshlrev_b32_e32 v21, 2, v20
	v_or_b32_e32 v23, 1600, v34
	s_mov_b64 exec, vcc
	global_store_dword v21, v23, s[2:3]
	s_mov_b64 exec, -1
	s_andn2_b64 s[0:1], s[0:1], vcc
	s_cbranch_scc1 .Lsel_eq25
.Lsel_eqb25:
	v_cmp_lt_u32_e32 vcc, s44, v114
	v_cmp_le_u32_e64 s[0:1], s37, v114
	s_bcnt1_i32_b64 s4, vcc
	v_mbcnt_lo_u32_b32 v20, vcc_lo, v18
	v_mbcnt_hi_u32_b32 v20, vcc_hi, v20
	v_add_u32_e32 v18, s4, v18
	v_lshlrev_b32_e32 v21, 2, v20
	v_or_b32_e32 v23, 1664, v34
	s_mov_b64 exec, vcc
	global_store_dword v21, v23, s[2:3]
	s_mov_b64 exec, -1
	s_andn2_b64 s[0:1], s[0:1], vcc
	s_cbranch_scc1 .Lsel_eq26
.Lsel_eqb26:
	v_cmp_lt_u32_e32 vcc, s44, v115
	v_cmp_le_u32_e64 s[0:1], s37, v115
	s_bcnt1_i32_b64 s4, vcc
	v_mbcnt_lo_u32_b32 v20, vcc_lo, v18
	v_mbcnt_hi_u32_b32 v20, vcc_hi, v20
	v_add_u32_e32 v18, s4, v18
	v_lshlrev_b32_e32 v21, 2, v20
	v_or_b32_e32 v23, 1728, v34
	s_mov_b64 exec, vcc
	global_store_dword v21, v23, s[2:3]
	s_mov_b64 exec, -1
	s_andn2_b64 s[0:1], s[0:1], vcc
	s_cbranch_scc1 .Lsel_eq27
.Lsel_eqb27:
	v_cmp_lt_u32_e32 vcc, s44, v116
	v_cmp_le_u32_e64 s[0:1], s37, v116
	s_bcnt1_i32_b64 s4, vcc
	v_mbcnt_lo_u32_b32 v20, vcc_lo, v18
	v_mbcnt_hi_u32_b32 v20, vcc_hi, v20
	v_add_u32_e32 v18, s4, v18
	v_lshlrev_b32_e32 v21, 2, v20
	v_or_b32_e32 v23, 1792, v34
	s_mov_b64 exec, vcc
	global_store_dword v21, v23, s[2:3]
	s_mov_b64 exec, -1
	s_andn2_b64 s[0:1], s[0:1], vcc
	s_cbranch_scc1 .Lsel_eq28
.Lsel_eqb28:
	v_cmp_lt_u32_e32 vcc, s44, v117
	v_cmp_le_u32_e64 s[0:1], s37, v117
	s_bcnt1_i32_b64 s4, vcc
	v_mbcnt_lo_u32_b32 v20, vcc_lo, v18
	v_mbcnt_hi_u32_b32 v20, vcc_hi, v20
	v_add_u32_e32 v18, s4, v18
	v_lshlrev_b32_e32 v21, 2, v20
	v_or_b32_e32 v23, 1856, v34
	s_mov_b64 exec, vcc
	global_store_dword v21, v23, s[2:3]
	s_mov_b64 exec, -1
	s_andn2_b64 s[0:1], s[0:1], vcc
	s_cbranch_scc1 .Lsel_eq29
.Lsel_eqb29:
	v_cmp_lt_u32_e32 vcc, s44, v118
	v_cmp_le_u32_e64 s[0:1], s37, v118
	s_bcnt1_i32_b64 s4, vcc
	v_mbcnt_lo_u32_b32 v20, vcc_lo, v18
	v_mbcnt_hi_u32_b32 v20, vcc_hi, v20
	v_add_u32_e32 v18, s4, v18
	v_lshlrev_b32_e32 v21, 2, v20
	v_or_b32_e32 v23, 1920, v34
	s_mov_b64 exec, vcc
	global_store_dword v21, v23, s[2:3]
	s_mov_b64 exec, -1
	s_andn2_b64 s[0:1], s[0:1], vcc
	s_cbranch_scc1 .Lsel_eq30
.Lsel_eqb30:
	v_cmp_lt_u32_e32 vcc, s44, v119
	v_cmp_le_u32_e64 s[0:1], s37, v119
	s_bcnt1_i32_b64 s4, vcc
	v_mbcnt_lo_u32_b32 v20, vcc_lo, v18
	v_mbcnt_hi_u32_b32 v20, vcc_hi, v20
	v_add_u32_e32 v18, s4, v18
	v_lshlrev_b32_e32 v21, 2, v20
	v_or_b32_e32 v23, 1984, v34
	s_mov_b64 exec, vcc
	global_store_dword v21, v23, s[2:3]
	s_mov_b64 exec, -1
	s_andn2_b64 s[0:1], s[0:1], vcc
	s_cbranch_scc1 .Lsel_eq31
.Lsel_eqb31:
	s_cmp_lt_i32 s38, 32
	s_cbranch_scc1 .Lsel_cp_done
	v_cmp_lt_u32_e32 vcc, s44, v120
	v_cmp_le_u32_e64 s[0:1], s37, v120
	s_bcnt1_i32_b64 s4, vcc
	v_mbcnt_lo_u32_b32 v20, vcc_lo, v18
	v_mbcnt_hi_u32_b32 v20, vcc_hi, v20
	v_add_u32_e32 v18, s4, v18
	v_lshlrev_b32_e32 v21, 2, v20
	v_or_b32_e32 v23, 2048, v34
	s_mov_b64 exec, vcc
	global_store_dword v21, v23, s[2:3]
	s_mov_b64 exec, -1
	s_andn2_b64 s[0:1], s[0:1], vcc
	s_cbranch_scc1 .Lsel_eq32
.Lsel_eqb32:
	v_cmp_lt_u32_e32 vcc, s44, v121
	v_cmp_le_u32_e64 s[0:1], s37, v121
	s_bcnt1_i32_b64 s4, vcc
	v_mbcnt_lo_u32_b32 v20, vcc_lo, v18
	v_mbcnt_hi_u32_b32 v20, vcc_hi, v20
	v_add_u32_e32 v18, s4, v18
	v_lshlrev_b32_e32 v21, 2, v20
	v_or_b32_e32 v23, 2112, v34
	s_mov_b64 exec, vcc
	global_store_dword v21, v23, s[2:3]
	s_mov_b64 exec, -1
	s_andn2_b64 s[0:1], s[0:1], vcc
	s_cbranch_scc1 .Lsel_eq33
.Lsel_eqb33:
	v_cmp_lt_u32_e32 vcc, s44, v122
	v_cmp_le_u32_e64 s[0:1], s37, v122
	s_bcnt1_i32_b64 s4, vcc
	v_mbcnt_lo_u32_b32 v20, vcc_lo, v18
	v_mbcnt_hi_u32_b32 v20, vcc_hi, v20
	v_add_u32_e32 v18, s4, v18
	v_lshlrev_b32_e32 v21, 2, v20
	v_or_b32_e32 v23, 2176, v34
	s_mov_b64 exec, vcc
	global_store_dword v21, v23, s[2:3]
	s_mov_b64 exec, -1
	s_andn2_b64 s[0:1], s[0:1], vcc
	s_cbranch_scc1 .Lsel_eq34
.Lsel_eqb34:
	v_cmp_lt_u32_e32 vcc, s44, v123
	v_cmp_le_u32_e64 s[0:1], s37, v123
	s_bcnt1_i32_b64 s4, vcc
	v_mbcnt_lo_u32_b32 v20, vcc_lo, v18
	v_mbcnt_hi_u32_b32 v20, vcc_hi, v20
	v_add_u32_e32 v18, s4, v18
	v_lshlrev_b32_e32 v21, 2, v20
	v_or_b32_e32 v23, 2240, v34
	s_mov_b64 exec, vcc
	global_store_dword v21, v23, s[2:3]
	s_mov_b64 exec, -1
	s_andn2_b64 s[0:1], s[0:1], vcc
	s_cbranch_scc1 .Lsel_eq35
.Lsel_eqb35:
	v_cmp_lt_u32_e32 vcc, s44, v124
	v_cmp_le_u32_e64 s[0:1], s37, v124
	s_bcnt1_i32_b64 s4, vcc
	v_mbcnt_lo_u32_b32 v20, vcc_lo, v18
	v_mbcnt_hi_u32_b32 v20, vcc_hi, v20
	v_add_u32_e32 v18, s4, v18
	v_lshlrev_b32_e32 v21, 2, v20
	v_or_b32_e32 v23, 2304, v34
	s_mov_b64 exec, vcc
	global_store_dword v21, v23, s[2:3]
	s_mov_b64 exec, -1
	s_andn2_b64 s[0:1], s[0:1], vcc
	s_cbranch_scc1 .Lsel_eq36
.Lsel_eqb36:
	v_cmp_lt_u32_e32 vcc, s44, v125
	v_cmp_le_u32_e64 s[0:1], s37, v125
	s_bcnt1_i32_b64 s4, vcc
	v_mbcnt_lo_u32_b32 v20, vcc_lo, v18
	v_mbcnt_hi_u32_b32 v20, vcc_hi, v20
	v_add_u32_e32 v18, s4, v18
	v_lshlrev_b32_e32 v21, 2, v20
	v_or_b32_e32 v23, 2368, v34
	s_mov_b64 exec, vcc
	global_store_dword v21, v23, s[2:3]
	s_mov_b64 exec, -1
	s_andn2_b64 s[0:1], s[0:1], vcc
	s_cbranch_scc1 .Lsel_eq37
.Lsel_eqb37:
	v_cmp_lt_u32_e32 vcc, s44, v126
	v_cmp_le_u32_e64 s[0:1], s37, v126
	s_bcnt1_i32_b64 s4, vcc
	v_mbcnt_lo_u32_b32 v20, vcc_lo, v18
	v_mbcnt_hi_u32_b32 v20, vcc_hi, v20
	v_add_u32_e32 v18, s4, v18
	v_lshlrev_b32_e32 v21, 2, v20
	v_or_b32_e32 v23, 2432, v34
	s_mov_b64 exec, vcc
	global_store_dword v21, v23, s[2:3]
	s_mov_b64 exec, -1
	s_andn2_b64 s[0:1], s[0:1], vcc
	s_cbranch_scc1 .Lsel_eq38
.Lsel_eqb38:
	v_cmp_lt_u32_e32 vcc, s44, v127
	v_cmp_le_u32_e64 s[0:1], s37, v127
	s_bcnt1_i32_b64 s4, vcc
	v_mbcnt_lo_u32_b32 v20, vcc_lo, v18
	v_mbcnt_hi_u32_b32 v20, vcc_hi, v20
	v_add_u32_e32 v18, s4, v18
	v_lshlrev_b32_e32 v21, 2, v20
	v_or_b32_e32 v23, 2496, v34
	s_mov_b64 exec, vcc
	global_store_dword v21, v23, s[2:3]
	s_mov_b64 exec, -1
	s_andn2_b64 s[0:1], s[0:1], vcc
	s_cbranch_scc1 .Lsel_eq39
.Lsel_eqb39:
	s_cmp_lt_i32 s38, 40
	s_cbranch_scc1 .Lsel_cp_done
	v_cmp_lt_u32_e32 vcc, s44, v128
	v_cmp_le_u32_e64 s[0:1], s37, v128
	s_bcnt1_i32_b64 s4, vcc
	v_mbcnt_lo_u32_b32 v20, vcc_lo, v18
	v_mbcnt_hi_u32_b32 v20, vcc_hi, v20
	v_add_u32_e32 v18, s4, v18
	v_lshlrev_b32_e32 v21, 2, v20
	v_or_b32_e32 v23, 2560, v34
	s_mov_b64 exec, vcc
	global_store_dword v21, v23, s[2:3]
	s_mov_b64 exec, -1
	s_andn2_b64 s[0:1], s[0:1], vcc
	s_cbranch_scc1 .Lsel_eq40
.Lsel_eqb40:
	v_cmp_lt_u32_e32 vcc, s44, v129
	v_cmp_le_u32_e64 s[0:1], s37, v129
	s_bcnt1_i32_b64 s4, vcc
	v_mbcnt_lo_u32_b32 v20, vcc_lo, v18
	v_mbcnt_hi_u32_b32 v20, vcc_hi, v20
	v_add_u32_e32 v18, s4, v18
	v_lshlrev_b32_e32 v21, 2, v20
	v_or_b32_e32 v23, 2624, v34
	s_mov_b64 exec, vcc
	global_store_dword v21, v23, s[2:3]
	s_mov_b64 exec, -1
	s_andn2_b64 s[0:1], s[0:1], vcc
	s_cbranch_scc1 .Lsel_eq41
.Lsel_eqb41:
	v_cmp_lt_u32_e32 vcc, s44, v130
	v_cmp_le_u32_e64 s[0:1], s37, v130
	s_bcnt1_i32_b64 s4, vcc
	v_mbcnt_lo_u32_b32 v20, vcc_lo, v18
	v_mbcnt_hi_u32_b32 v20, vcc_hi, v20
	v_add_u32_e32 v18, s4, v18
	v_lshlrev_b32_e32 v21, 2, v20
	v_or_b32_e32 v23, 2688, v34
	s_mov_b64 exec, vcc
	global_store_dword v21, v23, s[2:3]
	s_mov_b64 exec, -1
	s_andn2_b64 s[0:1], s[0:1], vcc
	s_cbranch_scc1 .Lsel_eq42
.Lsel_eqb42:
	v_cmp_lt_u32_e32 vcc, s44, v131
	v_cmp_le_u32_e64 s[0:1], s37, v131
	s_bcnt1_i32_b64 s4, vcc
	v_mbcnt_lo_u32_b32 v20, vcc_lo, v18
	v_mbcnt_hi_u32_b32 v20, vcc_hi, v20
	v_add_u32_e32 v18, s4, v18
	v_lshlrev_b32_e32 v21, 2, v20
	v_or_b32_e32 v23, 2752, v34
	s_mov_b64 exec, vcc
	global_store_dword v21, v23, s[2:3]
	s_mov_b64 exec, -1
	s_andn2_b64 s[0:1], s[0:1], vcc
	s_cbranch_scc1 .Lsel_eq43
.Lsel_eqb43:
	v_cmp_lt_u32_e32 vcc, s44, v132
	v_cmp_le_u32_e64 s[0:1], s37, v132
	s_bcnt1_i32_b64 s4, vcc
	v_mbcnt_lo_u32_b32 v20, vcc_lo, v18
	v_mbcnt_hi_u32_b32 v20, vcc_hi, v20
	v_add_u32_e32 v18, s4, v18
	v_lshlrev_b32_e32 v21, 2, v20
	v_or_b32_e32 v23, 2816, v34
	s_mov_b64 exec, vcc
	global_store_dword v21, v23, s[2:3]
	s_mov_b64 exec, -1
	s_andn2_b64 s[0:1], s[0:1], vcc
	s_cbranch_scc1 .Lsel_eq44
.Lsel_eqb44:
	v_cmp_lt_u32_e32 vcc, s44, v133
	v_cmp_le_u32_e64 s[0:1], s37, v133
	s_bcnt1_i32_b64 s4, vcc
	v_mbcnt_lo_u32_b32 v20, vcc_lo, v18
	v_mbcnt_hi_u32_b32 v20, vcc_hi, v20
	v_add_u32_e32 v18, s4, v18
	v_lshlrev_b32_e32 v21, 2, v20
	v_or_b32_e32 v23, 2880, v34
	s_mov_b64 exec, vcc
	global_store_dword v21, v23, s[2:3]
	s_mov_b64 exec, -1
	s_andn2_b64 s[0:1], s[0:1], vcc
	s_cbranch_scc1 .Lsel_eq45
.Lsel_eqb45:
	v_cmp_lt_u32_e32 vcc, s44, v134
	v_cmp_le_u32_e64 s[0:1], s37, v134
	s_bcnt1_i32_b64 s4, vcc
	v_mbcnt_lo_u32_b32 v20, vcc_lo, v18
	v_mbcnt_hi_u32_b32 v20, vcc_hi, v20
	v_add_u32_e32 v18, s4, v18
	v_lshlrev_b32_e32 v21, 2, v20
	v_or_b32_e32 v23, 2944, v34
	s_mov_b64 exec, vcc
	global_store_dword v21, v23, s[2:3]
	s_mov_b64 exec, -1
	s_andn2_b64 s[0:1], s[0:1], vcc
	s_cbranch_scc1 .Lsel_eq46
.Lsel_eqb46:
	v_cmp_lt_u32_e32 vcc, s44, v135
	v_cmp_le_u32_e64 s[0:1], s37, v135
	s_bcnt1_i32_b64 s4, vcc
	v_mbcnt_lo_u32_b32 v20, vcc_lo, v18
	v_mbcnt_hi_u32_b32 v20, vcc_hi, v20
	v_add_u32_e32 v18, s4, v18
	v_lshlrev_b32_e32 v21, 2, v20
	v_or_b32_e32 v23, 3008, v34
	s_mov_b64 exec, vcc
	global_store_dword v21, v23, s[2:3]
	s_mov_b64 exec, -1
	s_andn2_b64 s[0:1], s[0:1], vcc
	s_cbranch_scc1 .Lsel_eq47
.Lsel_eqb47:
	s_cmp_lt_i32 s38, 48
	s_cbranch_scc1 .Lsel_cp_done
	v_cmp_lt_u32_e32 vcc, s44, v136
	v_cmp_le_u32_e64 s[0:1], s37, v136
	s_bcnt1_i32_b64 s4, vcc
	v_mbcnt_lo_u32_b32 v20, vcc_lo, v18
	v_mbcnt_hi_u32_b32 v20, vcc_hi, v20
	v_add_u32_e32 v18, s4, v18
	v_lshlrev_b32_e32 v21, 2, v20
	v_or_b32_e32 v23, 3072, v34
	s_mov_b64 exec, vcc
	global_store_dword v21, v23, s[2:3]
	s_mov_b64 exec, -1
	s_andn2_b64 s[0:1], s[0:1], vcc
	s_cbranch_scc1 .Lsel_eq48
.Lsel_eqb48:
	v_cmp_lt_u32_e32 vcc, s44, v137
	v_cmp_le_u32_e64 s[0:1], s37, v137
	s_bcnt1_i32_b64 s4, vcc
	v_mbcnt_lo_u32_b32 v20, vcc_lo, v18
	v_mbcnt_hi_u32_b32 v20, vcc_hi, v20
	v_add_u32_e32 v18, s4, v18
	v_lshlrev_b32_e32 v21, 2, v20
	v_or_b32_e32 v23, 3136, v34
	s_mov_b64 exec, vcc
	global_store_dword v21, v23, s[2:3]
	s_mov_b64 exec, -1
	s_andn2_b64 s[0:1], s[0:1], vcc
	s_cbranch_scc1 .Lsel_eq49
.Lsel_eqb49:
	v_cmp_lt_u32_e32 vcc, s44, v138
	v_cmp_le_u32_e64 s[0:1], s37, v138
	s_bcnt1_i32_b64 s4, vcc
	v_mbcnt_lo_u32_b32 v20, vcc_lo, v18
	v_mbcnt_hi_u32_b32 v20, vcc_hi, v20
	v_add_u32_e32 v18, s4, v18
	v_lshlrev_b32_e32 v21, 2, v20
	v_or_b32_e32 v23, 3200, v34
	s_mov_b64 exec, vcc
	global_store_dword v21, v23, s[2:3]
	s_mov_b64 exec, -1
	s_andn2_b64 s[0:1], s[0:1], vcc
	s_cbranch_scc1 .Lsel_eq50
.Lsel_eqb50:
	v_cmp_lt_u32_e32 vcc, s44, v139
	v_cmp_le_u32_e64 s[0:1], s37, v139
	s_bcnt1_i32_b64 s4, vcc
	v_mbcnt_lo_u32_b32 v20, vcc_lo, v18
	v_mbcnt_hi_u32_b32 v20, vcc_hi, v20
	v_add_u32_e32 v18, s4, v18
	v_lshlrev_b32_e32 v21, 2, v20
	v_or_b32_e32 v23, 3264, v34
	s_mov_b64 exec, vcc
	global_store_dword v21, v23, s[2:3]
	s_mov_b64 exec, -1
	s_andn2_b64 s[0:1], s[0:1], vcc
	s_cbranch_scc1 .Lsel_eq51
.Lsel_eqb51:
	v_cmp_lt_u32_e32 vcc, s44, v140
	v_cmp_le_u32_e64 s[0:1], s37, v140
	s_bcnt1_i32_b64 s4, vcc
	v_mbcnt_lo_u32_b32 v20, vcc_lo, v18
	v_mbcnt_hi_u32_b32 v20, vcc_hi, v20
	v_add_u32_e32 v18, s4, v18
	v_lshlrev_b32_e32 v21, 2, v20
	v_or_b32_e32 v23, 3328, v34
	s_mov_b64 exec, vcc
	global_store_dword v21, v23, s[2:3]
	s_mov_b64 exec, -1
	s_andn2_b64 s[0:1], s[0:1], vcc
	s_cbranch_scc1 .Lsel_eq52
.Lsel_eqb52:
	v_cmp_lt_u32_e32 vcc, s44, v141
	v_cmp_le_u32_e64 s[0:1], s37, v141
	s_bcnt1_i32_b64 s4, vcc
	v_mbcnt_lo_u32_b32 v20, vcc_lo, v18
	v_mbcnt_hi_u32_b32 v20, vcc_hi, v20
	v_add_u32_e32 v18, s4, v18
	v_lshlrev_b32_e32 v21, 2, v20
	v_or_b32_e32 v23, 3392, v34
	s_mov_b64 exec, vcc
	global_store_dword v21, v23, s[2:3]
	s_mov_b64 exec, -1
	s_andn2_b64 s[0:1], s[0:1], vcc
	s_cbranch_scc1 .Lsel_eq53
.Lsel_eqb53:
	v_cmp_lt_u32_e32 vcc, s44, v142
	v_cmp_le_u32_e64 s[0:1], s37, v142
	s_bcnt1_i32_b64 s4, vcc
	v_mbcnt_lo_u32_b32 v20, vcc_lo, v18
	v_mbcnt_hi_u32_b32 v20, vcc_hi, v20
	v_add_u32_e32 v18, s4, v18
	v_lshlrev_b32_e32 v21, 2, v20
	v_or_b32_e32 v23, 3456, v34
	s_mov_b64 exec, vcc
	global_store_dword v21, v23, s[2:3]
	s_mov_b64 exec, -1
	s_andn2_b64 s[0:1], s[0:1], vcc
	s_cbranch_scc1 .Lsel_eq54
.Lsel_eqb54:
	v_cmp_lt_u32_e32 vcc, s44, v143
	v_cmp_le_u32_e64 s[0:1], s37, v143
	s_bcnt1_i32_b64 s4, vcc
	v_mbcnt_lo_u32_b32 v20, vcc_lo, v18
	v_mbcnt_hi_u32_b32 v20, vcc_hi, v20
	v_add_u32_e32 v18, s4, v18
	v_lshlrev_b32_e32 v21, 2, v20
	v_or_b32_e32 v23, 3520, v34
	s_mov_b64 exec, vcc
	global_store_dword v21, v23, s[2:3]
	s_mov_b64 exec, -1
	s_andn2_b64 s[0:1], s[0:1], vcc
	s_cbranch_scc1 .Lsel_eq55
.Lsel_eqb55:
	s_cmp_lt_i32 s38, 56
	s_cbranch_scc1 .Lsel_cp_done
	v_cmp_lt_u32_e32 vcc, s44, v144
	v_cmp_le_u32_e64 s[0:1], s37, v144
	s_bcnt1_i32_b64 s4, vcc
	v_mbcnt_lo_u32_b32 v20, vcc_lo, v18
	v_mbcnt_hi_u32_b32 v20, vcc_hi, v20
	v_add_u32_e32 v18, s4, v18
	v_lshlrev_b32_e32 v21, 2, v20
	v_or_b32_e32 v23, 3584, v34
	s_mov_b64 exec, vcc
	global_store_dword v21, v23, s[2:3]
	s_mov_b64 exec, -1
	s_andn2_b64 s[0:1], s[0:1], vcc
	s_cbranch_scc1 .Lsel_eq56
.Lsel_eqb56:
	v_cmp_lt_u32_e32 vcc, s44, v145
	v_cmp_le_u32_e64 s[0:1], s37, v145
	s_bcnt1_i32_b64 s4, vcc
	v_mbcnt_lo_u32_b32 v20, vcc_lo, v18
	v_mbcnt_hi_u32_b32 v20, vcc_hi, v20
	v_add_u32_e32 v18, s4, v18
	v_lshlrev_b32_e32 v21, 2, v20
	v_or_b32_e32 v23, 3648, v34
	s_mov_b64 exec, vcc
	global_store_dword v21, v23, s[2:3]
	s_mov_b64 exec, -1
	s_andn2_b64 s[0:1], s[0:1], vcc
	s_cbranch_scc1 .Lsel_eq57
.Lsel_eqb57:
	v_cmp_lt_u32_e32 vcc, s44, v146
	v_cmp_le_u32_e64 s[0:1], s37, v146
	s_bcnt1_i32_b64 s4, vcc
	v_mbcnt_lo_u32_b32 v20, vcc_lo, v18
	v_mbcnt_hi_u32_b32 v20, vcc_hi, v20
	v_add_u32_e32 v18, s4, v18
	v_lshlrev_b32_e32 v21, 2, v20
	v_or_b32_e32 v23, 3712, v34
	s_mov_b64 exec, vcc
	global_store_dword v21, v23, s[2:3]
	s_mov_b64 exec, -1
	s_andn2_b64 s[0:1], s[0:1], vcc
	s_cbranch_scc1 .Lsel_eq58
.Lsel_eqb58:
	v_cmp_lt_u32_e32 vcc, s44, v147
	v_cmp_le_u32_e64 s[0:1], s37, v147
	s_bcnt1_i32_b64 s4, vcc
	v_mbcnt_lo_u32_b32 v20, vcc_lo, v18
	v_mbcnt_hi_u32_b32 v20, vcc_hi, v20
	v_add_u32_e32 v18, s4, v18
	v_lshlrev_b32_e32 v21, 2, v20
	v_or_b32_e32 v23, 3776, v34
	s_mov_b64 exec, vcc
	global_store_dword v21, v23, s[2:3]
	s_mov_b64 exec, -1
	s_andn2_b64 s[0:1], s[0:1], vcc
	s_cbranch_scc1 .Lsel_eq59
.Lsel_eqb59:
	v_cmp_lt_u32_e32 vcc, s44, v148
	v_cmp_le_u32_e64 s[0:1], s37, v148
	s_bcnt1_i32_b64 s4, vcc
	v_mbcnt_lo_u32_b32 v20, vcc_lo, v18
	v_mbcnt_hi_u32_b32 v20, vcc_hi, v20
	v_add_u32_e32 v18, s4, v18
	v_lshlrev_b32_e32 v21, 2, v20
	v_or_b32_e32 v23, 3840, v34
	s_mov_b64 exec, vcc
	global_store_dword v21, v23, s[2:3]
	s_mov_b64 exec, -1
	s_andn2_b64 s[0:1], s[0:1], vcc
	s_cbranch_scc1 .Lsel_eq60
.Lsel_eqb60:
	v_cmp_lt_u32_e32 vcc, s44, v149
	v_cmp_le_u32_e64 s[0:1], s37, v149
	s_bcnt1_i32_b64 s4, vcc
	v_mbcnt_lo_u32_b32 v20, vcc_lo, v18
	v_mbcnt_hi_u32_b32 v20, vcc_hi, v20
	v_add_u32_e32 v18, s4, v18
	v_lshlrev_b32_e32 v21, 2, v20
	v_or_b32_e32 v23, 3904, v34
	s_mov_b64 exec, vcc
	global_store_dword v21, v23, s[2:3]
	s_mov_b64 exec, -1
	s_andn2_b64 s[0:1], s[0:1], vcc
	s_cbranch_scc1 .Lsel_eq61
.Lsel_eqb61:
	v_cmp_lt_u32_e32 vcc, s44, v150
	v_cmp_le_u32_e64 s[0:1], s37, v150
	s_bcnt1_i32_b64 s4, vcc
	v_mbcnt_lo_u32_b32 v20, vcc_lo, v18
	v_mbcnt_hi_u32_b32 v20, vcc_hi, v20
	v_add_u32_e32 v18, s4, v18
	v_lshlrev_b32_e32 v21, 2, v20
	v_or_b32_e32 v23, 3968, v34
	s_mov_b64 exec, vcc
	global_store_dword v21, v23, s[2:3]
	s_mov_b64 exec, -1
	s_andn2_b64 s[0:1], s[0:1], vcc
	s_cbranch_scc1 .Lsel_eq62
.Lsel_eqb62:
	v_cmp_lt_u32_e32 vcc, s44, v151
	v_cmp_le_u32_e64 s[0:1], s37, v151
	s_bcnt1_i32_b64 s4, vcc
	v_mbcnt_lo_u32_b32 v20, vcc_lo, v18
	v_mbcnt_hi_u32_b32 v20, vcc_hi, v20
	v_add_u32_e32 v18, s4, v18
	v_lshlrev_b32_e32 v21, 2, v20
	v_or_b32_e32 v23, 4032, v34
	s_mov_b64 exec, vcc
	global_store_dword v21, v23, s[2:3]
	s_mov_b64 exec, -1
	s_andn2_b64 s[0:1], s[0:1], vcc
	s_cbranch_scc1 .Lsel_eq63

.Lsel_eq0:
	v_mbcnt_lo_u32_b32 v20, s0, v19
	v_mbcnt_hi_u32_b32 v20, s1, v20
	s_bcnt1_i32_b64 s4, s[0:1]
	v_cmp_gt_u32_e32 vcc, 0x100, v20
	v_lshlrev_b32_e32 v21, 2, v20
	v_add_u32_e32 v19, s4, v19
	s_and_b64 exec, vcc, s[0:1]
	global_store_dword v21, v23, s[2:3]
	s_mov_b64 exec, -1
	s_branch .Lsel_eqb0
